# gdn_prep forward substitution: each row's serial FMA chain split into 3 independent partial sums
# speedup vs baseline: 1.1654x; 1.0010x over previous
.LBB0_313:
	s_or_b64 exec, exec, s[0:1]
	ds_read_b32 v0, v1 offset:16640
	s_waitcnt lgkmcnt(0)
	v_fma_f32 v3, -v2, v0, v3
	ds_read_b64 v[122:123], v1 offset:16896
	s_waitcnt lgkmcnt(0)
	v_fma_f32 v0, -v2, v122, v50
	v_mul_f32_e64 v254, -v123, v3
	v_add_f32_e32 v9, v0, v254
	ds_read_b96 v[122:124], v1 offset:17152
	s_waitcnt lgkmcnt(0)
	v_fma_f32 v0, -v2, v122, v51
	v_mul_f32_e64 v254, -v3, v123
	v_mul_f32_e64 v255, -v124, v9
	v_add_f32_e32 v254, v0, v254
	v_add_f32_e32 v50, v254, v255
	ds_read_b128 v[122:125], v1 offset:17408
	s_waitcnt lgkmcnt(0)
	v_fma_f32 v0, -v2, v122, v54
	v_mul_f32_e64 v254, -v3, v123
	v_mul_f32_e64 v255, -v9, v124
	v_fma_f32 v0, -v125, v50, v0
	v_add_f32_e32 v254, v0, v254
	v_add_f32_e32 v51, v254, v255
	ds_read_b128 v[122:125], v1 offset:17664
	ds_read_b32 v0, v1 offset:17680
	s_waitcnt lgkmcnt(1)
	v_fma_f32 v54, -v2, v122, v55
	v_mul_f32_e64 v254, -v3, v123
	v_mul_f32_e64 v255, -v9, v124
	v_fma_f32 v54, -v50, v125, v54
	s_waitcnt lgkmcnt(0)
	v_fma_f32 v254, -v51, v0, v254
	v_add_f32_e32 v254, v54, v254
	v_add_f32_e32 v54, v254, v255
	ds_read_b128 v[122:125], v1 offset:17920
	ds_read_b64 v[126:127], v1 offset:17936
	s_waitcnt lgkmcnt(1)
	v_fma_f32 v0, -v2, v122, v56
	v_mul_f32_e64 v254, -v3, v123
	v_mul_f32_e64 v255, -v9, v124
	v_fma_f32 v0, -v50, v125, v0
	s_waitcnt lgkmcnt(0)
	v_fma_f32 v254, -v51, v126, v254
	v_fma_f32 v255, -v54, v127, v255
	v_add_f32_e32 v254, v0, v254
	v_add_f32_e32 v55, v254, v255
	ds_read_b128 v[122:125], v1 offset:18176
	ds_read_b96 v[126:128], v1 offset:18192
	s_waitcnt lgkmcnt(1)
	v_fma_f32 v0, -v2, v122, v57
	v_mul_f32_e64 v254, -v3, v123
	v_mul_f32_e64 v255, -v9, v124
	v_fma_f32 v0, -v50, v125, v0
	s_waitcnt lgkmcnt(0)
	v_fma_f32 v254, -v51, v126, v254
	v_fma_f32 v255, -v54, v127, v255
	v_fma_f32 v0, -v55, v128, v0
	v_add_f32_e32 v254, v0, v254
	v_add_f32_e32 v56, v254, v255
	ds_read_b128 v[122:125], v1 offset:18432
	ds_read_b128 v[126:129], v1 offset:18448
	s_waitcnt lgkmcnt(1)
	v_fma_f32 v0, -v2, v122, v58
	v_mul_f32_e64 v254, -v3, v123
	v_mul_f32_e64 v255, -v9, v124
	v_fma_f32 v0, -v50, v125, v0
	s_waitcnt lgkmcnt(0)
	v_fma_f32 v254, -v51, v126, v254
	v_fma_f32 v255, -v54, v127, v255
	v_fma_f32 v0, -v55, v128, v0
	v_fma_f32 v254, -v56, v129, v254
	v_add_f32_e32 v254, v0, v254
	v_add_f32_e32 v57, v254, v255
	ds_read_b128 v[122:125], v1 offset:18688
	ds_read_b128 v[126:129], v1 offset:18704
	ds_read_b32 v0, v1 offset:18720
	s_waitcnt lgkmcnt(2)
	v_fma_f32 v58, -v2, v122, v59
	v_mul_f32_e64 v254, -v3, v123
	v_mul_f32_e64 v255, -v9, v124
	v_fma_f32 v58, -v50, v125, v58
	s_waitcnt lgkmcnt(1)
	v_fma_f32 v254, -v51, v126, v254
	v_fma_f32 v255, -v54, v127, v255
	v_fma_f32 v58, -v55, v128, v58
	v_fma_f32 v254, -v56, v129, v254
	s_waitcnt lgkmcnt(0)
	v_fma_f32 v255, -v57, v0, v255
	v_add_f32_e32 v254, v58, v254
	v_add_f32_e32 v58, v254, v255
	ds_read_b128 v[122:125], v1 offset:18944
	ds_read_b128 v[126:129], v1 offset:18960
	ds_read_b64 v[130:131], v1 offset:18976
	s_waitcnt lgkmcnt(2)
	v_fma_f32 v0, -v2, v122, v60
	v_mul_f32_e64 v254, -v3, v123
	v_mul_f32_e64 v255, -v9, v124
	v_fma_f32 v0, -v50, v125, v0
	s_waitcnt lgkmcnt(1)
	v_fma_f32 v254, -v51, v126, v254
	v_fma_f32 v255, -v54, v127, v255
	v_fma_f32 v0, -v55, v128, v0
	v_fma_f32 v254, -v56, v129, v254
	s_waitcnt lgkmcnt(0)
	v_fma_f32 v255, -v57, v130, v255
	v_fma_f32 v0, -v58, v131, v0
	v_add_f32_e32 v254, v0, v254
	v_add_f32_e32 v59, v254, v255
	ds_read_b128 v[122:125], v1 offset:19200
	ds_read_b128 v[126:129], v1 offset:19216
	ds_read_b96 v[130:132], v1 offset:19232
	s_waitcnt lgkmcnt(2)
	v_fma_f32 v0, -v2, v122, v61
	v_mul_f32_e64 v254, -v3, v123
	v_mul_f32_e64 v255, -v9, v124
	v_fma_f32 v0, -v50, v125, v0
	s_waitcnt lgkmcnt(1)
	v_fma_f32 v254, -v51, v126, v254
	v_fma_f32 v255, -v54, v127, v255
	v_fma_f32 v0, -v55, v128, v0
	v_fma_f32 v254, -v56, v129, v254
	s_waitcnt lgkmcnt(0)
	v_fma_f32 v255, -v57, v130, v255
	v_fma_f32 v0, -v58, v131, v0
	v_fma_f32 v254, -v59, v132, v254
	v_add_f32_e32 v254, v0, v254
	v_add_f32_e32 v60, v254, v255
	ds_read_b128 v[122:125], v1 offset:19456
	ds_read_b128 v[126:129], v1 offset:19472
	ds_read_b128 v[130:133], v1 offset:19488
	s_waitcnt lgkmcnt(2)
	v_fma_f32 v0, -v2, v122, v62
	v_mul_f32_e64 v254, -v3, v123
	v_mul_f32_e64 v255, -v9, v124
	v_fma_f32 v0, -v50, v125, v0
	s_waitcnt lgkmcnt(1)
	v_fma_f32 v254, -v51, v126, v254
	v_fma_f32 v255, -v54, v127, v255
	v_fma_f32 v0, -v55, v128, v0
	v_fma_f32 v254, -v56, v129, v254
	s_waitcnt lgkmcnt(0)
	v_fma_f32 v255, -v57, v130, v255
	v_fma_f32 v0, -v58, v131, v0
	v_fma_f32 v254, -v59, v132, v254
	v_fma_f32 v255, -v60, v133, v255
	v_add_f32_e32 v254, v0, v254
	v_add_f32_e32 v61, v254, v255
	ds_read_b128 v[122:125], v1 offset:19712
	ds_read_b128 v[126:129], v1 offset:19728
	ds_read_b128 v[130:133], v1 offset:19744
	ds_read_b32 v0, v1 offset:19760
	s_waitcnt lgkmcnt(3)
	v_fma_f32 v62, -v2, v122, v63
	v_mul_f32_e64 v254, -v3, v123
	v_mul_f32_e64 v255, -v9, v124
	v_fma_f32 v62, -v50, v125, v62
	s_waitcnt lgkmcnt(2)
	v_fma_f32 v254, -v51, v126, v254
	v_fma_f32 v255, -v54, v127, v255
	v_fma_f32 v62, -v55, v128, v62
	v_fma_f32 v254, -v56, v129, v254
	s_waitcnt lgkmcnt(1)
	v_fma_f32 v255, -v57, v130, v255
	v_fma_f32 v62, -v58, v131, v62
	v_fma_f32 v254, -v59, v132, v254
	v_fma_f32 v255, -v60, v133, v255
	s_waitcnt lgkmcnt(0)
	v_fma_f32 v62, -v61, v0, v62
	v_add_f32_e32 v254, v62, v254
	v_add_f32_e32 v62, v254, v255
	ds_read_b128 v[122:125], v1 offset:19968
	ds_read_b128 v[126:129], v1 offset:19984
	ds_read_b128 v[130:133], v1 offset:20000
	ds_read_b64 v[134:135], v1 offset:20016
	s_waitcnt lgkmcnt(3)
	v_fma_f32 v0, -v2, v122, v70
	v_mul_f32_e64 v254, -v3, v123
	v_mul_f32_e64 v255, -v9, v124
	v_fma_f32 v0, -v50, v125, v0
	s_waitcnt lgkmcnt(2)
	v_fma_f32 v254, -v51, v126, v254
	v_fma_f32 v255, -v54, v127, v255
	v_fma_f32 v0, -v55, v128, v0
	v_fma_f32 v254, -v56, v129, v254
	s_waitcnt lgkmcnt(1)
	v_fma_f32 v255, -v57, v130, v255
	v_fma_f32 v0, -v58, v131, v0
	v_fma_f32 v254, -v59, v132, v254
	v_fma_f32 v255, -v60, v133, v255
	s_waitcnt lgkmcnt(0)
	v_fma_f32 v0, -v61, v134, v0
	v_fma_f32 v254, -v62, v135, v254
	v_add_f32_e32 v254, v0, v254
	v_add_f32_e32 v63, v254, v255
	ds_read_b128 v[122:125], v1 offset:20224
	ds_read_b128 v[126:129], v1 offset:20240
	ds_read_b128 v[130:133], v1 offset:20256
	ds_read_b96 v[216:218], v1 offset:20272
	s_waitcnt lgkmcnt(3)
	v_fma_f32 v0, -v2, v122, v71
	v_mul_f32_e64 v254, -v3, v123
	v_mul_f32_e64 v255, -v9, v124
	v_fma_f32 v0, -v50, v125, v0
	s_waitcnt lgkmcnt(2)
	v_fma_f32 v254, -v51, v126, v254
	v_fma_f32 v255, -v54, v127, v255
	v_fma_f32 v0, -v55, v128, v0
	v_fma_f32 v254, -v56, v129, v254
	s_waitcnt lgkmcnt(1)
	v_fma_f32 v255, -v57, v130, v255
	v_fma_f32 v0, -v58, v131, v0
	v_fma_f32 v254, -v59, v132, v254
	v_fma_f32 v255, -v60, v133, v255
	s_waitcnt lgkmcnt(0)
	v_fma_f32 v0, -v61, v216, v0
	v_fma_f32 v254, -v62, v217, v254
	v_fma_f32 v255, -v63, v218, v255
	v_add_f32_e32 v254, v0, v254
	v_add_f32_e32 v70, v254, v255
	ds_read_b128 v[122:125], v1 offset:20480
	ds_read_b128 v[126:129], v1 offset:20496
	ds_read_b128 v[130:133], v1 offset:20512
	ds_read_b128 v[220:223], v1 offset:20528
	s_waitcnt lgkmcnt(3)
	v_fma_f32 v0, -v2, v122, v68
	v_mul_f32_e64 v254, -v3, v123
	v_mul_f32_e64 v255, -v9, v124
	v_fma_f32 v0, -v50, v125, v0
	s_waitcnt lgkmcnt(2)
	v_fma_f32 v254, -v51, v126, v254
	v_fma_f32 v255, -v54, v127, v255
	v_fma_f32 v0, -v55, v128, v0
	v_fma_f32 v254, -v56, v129, v254
	s_waitcnt lgkmcnt(1)
	v_fma_f32 v255, -v57, v130, v255
	v_fma_f32 v0, -v58, v131, v0
	v_fma_f32 v254, -v59, v132, v254
	v_fma_f32 v255, -v60, v133, v255
	s_waitcnt lgkmcnt(0)
	v_fma_f32 v0, -v61, v220, v0
	v_fma_f32 v254, -v62, v221, v254
	v_fma_f32 v255, -v63, v222, v255
	v_fma_f32 v0, -v70, v223, v0
	v_add_f32_e32 v254, v0, v254
	v_add_f32_e32 v68, v254, v255
	ds_read_b128 v[122:125], v1 offset:20736
	ds_read_b128 v[126:129], v1 offset:20752
	ds_read_b128 v[130:133], v1 offset:20768
	ds_read_b128 v[220:223], v1 offset:20784
	s_waitcnt lgkmcnt(3)
	v_fma_f32 v0, -v2, v122, v69
	v_mul_f32_e64 v254, -v3, v123
	v_mul_f32_e64 v255, -v9, v124
	v_fma_f32 v0, -v50, v125, v0
	s_waitcnt lgkmcnt(2)
	v_fma_f32 v254, -v51, v126, v254
	v_fma_f32 v255, -v54, v127, v255
	v_fma_f32 v0, -v55, v128, v0
	v_fma_f32 v254, -v56, v129, v254
	s_waitcnt lgkmcnt(1)
	v_fma_f32 v255, -v57, v130, v255
	v_fma_f32 v0, -v58, v131, v0
	v_fma_f32 v254, -v59, v132, v254
	v_fma_f32 v255, -v60, v133, v255
	ds_read_b32 v69, v1 offset:20800
	s_waitcnt lgkmcnt(1)
	v_fma_f32 v0, -v61, v220, v0
	v_fma_f32 v254, -v62, v221, v254
	v_fma_f32 v255, -v63, v222, v255
	v_fma_f32 v0, -v70, v223, v0
	s_waitcnt lgkmcnt(0)
	v_fma_f32 v254, -v68, v69, v254
	v_add_f32_e32 v254, v0, v254
	v_add_f32_e32 v69, v254, v255
	ds_read_b128 v[122:125], v1 offset:20992
	ds_read_b128 v[126:129], v1 offset:21008
	ds_read_b128 v[130:133], v1 offset:21024
	ds_read_b128 v[220:223], v1 offset:21040
	s_waitcnt lgkmcnt(3)
	v_fma_f32 v0, -v2, v122, v66
	v_mul_f32_e64 v254, -v3, v123
	v_mul_f32_e64 v255, -v9, v124
	v_fma_f32 v0, -v50, v125, v0
	s_waitcnt lgkmcnt(2)
	v_fma_f32 v254, -v51, v126, v254
	v_fma_f32 v255, -v54, v127, v255
	v_fma_f32 v0, -v55, v128, v0
	v_fma_f32 v254, -v56, v129, v254
	s_waitcnt lgkmcnt(1)
	v_fma_f32 v255, -v57, v130, v255
	v_fma_f32 v0, -v58, v131, v0
	v_fma_f32 v254, -v59, v132, v254
	v_fma_f32 v255, -v60, v133, v255
	ds_read_b64 v[122:123], v1 offset:21056
	s_waitcnt lgkmcnt(1)
	v_fma_f32 v0, -v61, v220, v0
	v_fma_f32 v254, -v62, v221, v254
	v_fma_f32 v255, -v63, v222, v255
	v_fma_f32 v0, -v70, v223, v0
	s_waitcnt lgkmcnt(0)
	v_fma_f32 v254, -v68, v122, v254
	v_fma_f32 v255, -v69, v123, v255
	v_add_f32_e32 v254, v0, v254
	v_add_f32_e32 v66, v254, v255
	ds_read_b128 v[122:125], v1 offset:21248
	ds_read_b128 v[126:129], v1 offset:21264
	ds_read_b128 v[130:133], v1 offset:21280
	ds_read_b128 v[220:223], v1 offset:21296
	s_waitcnt lgkmcnt(3)
	v_fma_f32 v0, -v2, v122, v67
	v_mul_f32_e64 v254, -v3, v123
	v_mul_f32_e64 v255, -v9, v124
	v_fma_f32 v0, -v50, v125, v0
	s_waitcnt lgkmcnt(2)
	v_fma_f32 v254, -v51, v126, v254
	v_fma_f32 v255, -v54, v127, v255
	v_fma_f32 v0, -v55, v128, v0
	v_fma_f32 v254, -v56, v129, v254
	s_waitcnt lgkmcnt(1)
	v_fma_f32 v255, -v57, v130, v255
	v_fma_f32 v0, -v58, v131, v0
	v_fma_f32 v254, -v59, v132, v254
	v_fma_f32 v255, -v60, v133, v255
	ds_read_b96 v[122:124], v1 offset:21312
	s_waitcnt lgkmcnt(1)
	v_fma_f32 v0, -v61, v220, v0
	v_fma_f32 v254, -v62, v221, v254
	v_fma_f32 v255, -v63, v222, v255
	v_fma_f32 v0, -v70, v223, v0
	s_waitcnt lgkmcnt(0)
	v_fma_f32 v254, -v68, v122, v254
	v_fma_f32 v255, -v69, v123, v255
	v_fma_f32 v0, -v66, v124, v0
	v_add_f32_e32 v254, v0, v254
	v_add_f32_e32 v67, v254, v255
	ds_read_b128 v[122:125], v1 offset:21504
	ds_read_b128 v[126:129], v1 offset:21520
	ds_read_b128 v[130:133], v1 offset:21536
	ds_read_b128 v[220:223], v1 offset:21552
	s_waitcnt lgkmcnt(3)
	v_fma_f32 v0, -v2, v122, v64
	v_mul_f32_e64 v254, -v3, v123
	v_mul_f32_e64 v255, -v9, v124
	v_fma_f32 v0, -v50, v125, v0
	s_waitcnt lgkmcnt(2)
	v_fma_f32 v254, -v51, v126, v254
	v_fma_f32 v255, -v54, v127, v255
	v_fma_f32 v0, -v55, v128, v0
	v_fma_f32 v254, -v56, v129, v254
	s_waitcnt lgkmcnt(1)
	v_fma_f32 v255, -v57, v130, v255
	v_fma_f32 v0, -v58, v131, v0
	v_fma_f32 v254, -v59, v132, v254
	v_fma_f32 v255, -v60, v133, v255
	ds_read_b128 v[122:125], v1 offset:21568
	s_waitcnt lgkmcnt(1)
	v_fma_f32 v0, -v61, v220, v0
	v_fma_f32 v254, -v62, v221, v254
	v_fma_f32 v255, -v63, v222, v255
	v_fma_f32 v0, -v70, v223, v0
	s_waitcnt lgkmcnt(0)
	v_fma_f32 v254, -v68, v122, v254
	v_fma_f32 v255, -v69, v123, v255
	v_fma_f32 v0, -v66, v124, v0
	v_fma_f32 v254, -v67, v125, v254
	v_add_f32_e32 v254, v0, v254
	v_add_f32_e32 v64, v254, v255
	ds_read_b128 v[122:125], v1 offset:21760
	ds_read_b128 v[126:129], v1 offset:21776
	ds_read_b128 v[130:133], v1 offset:21792
	ds_read_b128 v[220:223], v1 offset:21808
	s_waitcnt lgkmcnt(3)
	v_fma_f32 v0, -v2, v122, v65
	v_mul_f32_e64 v254, -v3, v123
	v_mul_f32_e64 v255, -v9, v124
	v_fma_f32 v0, -v50, v125, v0
	s_waitcnt lgkmcnt(2)
	v_fma_f32 v254, -v51, v126, v254
	v_fma_f32 v255, -v54, v127, v255
	v_fma_f32 v0, -v55, v128, v0
	v_fma_f32 v254, -v56, v129, v254
	s_waitcnt lgkmcnt(1)
	v_fma_f32 v255, -v57, v130, v255
	v_fma_f32 v0, -v58, v131, v0
	v_fma_f32 v254, -v59, v132, v254
	v_fma_f32 v255, -v60, v133, v255
	ds_read_b128 v[122:125], v1 offset:21824
	ds_read_b32 v65, v1 offset:21840
	s_waitcnt lgkmcnt(2)
	v_fma_f32 v0, -v61, v220, v0
	v_fma_f32 v254, -v62, v221, v254
	v_fma_f32 v255, -v63, v222, v255
	v_fma_f32 v0, -v70, v223, v0
	s_waitcnt lgkmcnt(1)
	v_fma_f32 v254, -v68, v122, v254
	v_fma_f32 v255, -v69, v123, v255
	v_fma_f32 v0, -v66, v124, v0
	v_fma_f32 v254, -v67, v125, v254
	s_waitcnt lgkmcnt(0)
	v_fma_f32 v255, -v64, v65, v255
	v_add_f32_e32 v254, v0, v254
	v_add_f32_e32 v65, v254, v255
	ds_read_b128 v[122:125], v1 offset:22016
	ds_read_b128 v[126:129], v1 offset:22032
	ds_read_b128 v[130:133], v1 offset:22048
	ds_read_b128 v[220:223], v1 offset:22064
	s_waitcnt lgkmcnt(3)
	v_fma_f32 v0, -v2, v122, v52
	v_mul_f32_e64 v254, -v3, v123
	v_mul_f32_e64 v255, -v9, v124
	v_fma_f32 v0, -v50, v125, v0
	s_waitcnt lgkmcnt(2)
	v_fma_f32 v254, -v51, v126, v254
	v_fma_f32 v255, -v54, v127, v255
	v_fma_f32 v0, -v55, v128, v0
	v_fma_f32 v254, -v56, v129, v254
	s_waitcnt lgkmcnt(1)
	v_fma_f32 v255, -v57, v130, v255
	v_fma_f32 v0, -v58, v131, v0
	v_fma_f32 v254, -v59, v132, v254
	v_fma_f32 v255, -v60, v133, v255
	ds_read_b128 v[122:125], v1 offset:22080
	s_waitcnt lgkmcnt(1)
	v_fma_f32 v0, -v61, v220, v0
	v_fma_f32 v254, -v62, v221, v254
	v_fma_f32 v255, -v63, v222, v255
	v_fma_f32 v0, -v70, v223, v0
	s_waitcnt lgkmcnt(0)
	v_fma_f32 v254, -v68, v122, v254
	v_fma_f32 v255, -v69, v123, v255
	ds_read_b64 v[122:123], v1 offset:22096
	v_fma_f32 v0, -v66, v124, v0
	v_fma_f32 v254, -v67, v125, v254
	s_waitcnt lgkmcnt(0)
	v_fma_f32 v255, -v64, v122, v255
	v_fma_f32 v0, -v65, v123, v0
	v_add_f32_e32 v254, v0, v254
	v_add_f32_e32 v52, v254, v255
	ds_read_b128 v[122:125], v1 offset:22272
	ds_read_b128 v[126:129], v1 offset:22288
	ds_read_b128 v[130:133], v1 offset:22304
	ds_read_b128 v[220:223], v1 offset:22320
	s_waitcnt lgkmcnt(3)
	v_fma_f32 v0, -v2, v122, v53
	v_mul_f32_e64 v254, -v3, v123
	v_mul_f32_e64 v255, -v9, v124
	v_fma_f32 v0, -v50, v125, v0
	s_waitcnt lgkmcnt(2)
	v_fma_f32 v254, -v51, v126, v254
	v_fma_f32 v255, -v54, v127, v255
	v_fma_f32 v0, -v55, v128, v0
	v_fma_f32 v254, -v56, v129, v254
	s_waitcnt lgkmcnt(1)
	v_fma_f32 v255, -v57, v130, v255
	v_fma_f32 v0, -v58, v131, v0
	v_fma_f32 v254, -v59, v132, v254
	v_fma_f32 v255, -v60, v133, v255
	ds_read_b128 v[122:125], v1 offset:22336
	s_waitcnt lgkmcnt(1)
	v_fma_f32 v0, -v61, v220, v0
	v_fma_f32 v254, -v62, v221, v254
	v_fma_f32 v255, -v63, v222, v255
	v_fma_f32 v0, -v70, v223, v0
	s_waitcnt lgkmcnt(0)
	v_fma_f32 v254, -v68, v122, v254
	v_fma_f32 v255, -v69, v123, v255
	v_fma_f32 v0, -v66, v124, v0
	ds_read_b96 v[122:124], v1 offset:22352
	v_fma_f32 v254, -v67, v125, v254
	s_waitcnt lgkmcnt(0)
	v_fma_f32 v255, -v64, v122, v255
	v_fma_f32 v0, -v65, v123, v0
	v_fma_f32 v254, -v52, v124, v254
	v_add_f32_e32 v254, v0, v254
	v_add_f32_e32 v53, v254, v255
	ds_read_b128 v[122:125], v1 offset:22528
	ds_read_b128 v[126:129], v1 offset:22544
	ds_read_b128 v[130:133], v1 offset:22560
	ds_read_b128 v[220:223], v1 offset:22576
	s_waitcnt lgkmcnt(3)
	v_fma_f32 v0, -v2, v122, v48
	v_mul_f32_e64 v254, -v3, v123
	v_mul_f32_e64 v255, -v9, v124
	v_fma_f32 v0, -v50, v125, v0
	s_waitcnt lgkmcnt(2)
	v_fma_f32 v254, -v51, v126, v254
	v_fma_f32 v255, -v54, v127, v255
	v_fma_f32 v0, -v55, v128, v0
	v_fma_f32 v254, -v56, v129, v254
	s_waitcnt lgkmcnt(1)
	v_fma_f32 v255, -v57, v130, v255
	v_fma_f32 v0, -v58, v131, v0
	v_fma_f32 v254, -v59, v132, v254
	v_fma_f32 v255, -v60, v133, v255
	ds_read_b128 v[122:125], v1 offset:22592
	s_waitcnt lgkmcnt(1)
	v_fma_f32 v0, -v61, v220, v0
	v_fma_f32 v254, -v62, v221, v254
	v_fma_f32 v255, -v63, v222, v255
	v_fma_f32 v0, -v70, v223, v0
	s_waitcnt lgkmcnt(0)
	v_fma_f32 v254, -v68, v122, v254
	v_fma_f32 v255, -v69, v123, v255
	v_fma_f32 v0, -v66, v124, v0
	v_fma_f32 v254, -v67, v125, v254
	ds_read_b128 v[122:125], v1 offset:22608
	s_waitcnt lgkmcnt(0)
	v_fma_f32 v255, -v64, v122, v255
	v_fma_f32 v0, -v65, v123, v0
	v_fma_f32 v254, -v52, v124, v254
	v_fma_f32 v255, -v53, v125, v255
	v_add_f32_e32 v254, v0, v254
	v_add_f32_e32 v48, v254, v255
	ds_read_b128 v[122:125], v1 offset:22784
	ds_read_b128 v[126:129], v1 offset:22800
	ds_read_b128 v[130:133], v1 offset:22816
	ds_read_b128 v[220:223], v1 offset:22832
	s_waitcnt lgkmcnt(3)
	v_fma_f32 v0, -v2, v122, v49
	v_mul_f32_e64 v254, -v3, v123
	v_mul_f32_e64 v255, -v9, v124
	v_fma_f32 v0, -v50, v125, v0
	s_waitcnt lgkmcnt(2)
	v_fma_f32 v254, -v51, v126, v254
	v_fma_f32 v255, -v54, v127, v255
	v_fma_f32 v0, -v55, v128, v0
	v_fma_f32 v254, -v56, v129, v254
	s_waitcnt lgkmcnt(1)
	v_fma_f32 v255, -v57, v130, v255
	v_fma_f32 v0, -v58, v131, v0
	v_fma_f32 v254, -v59, v132, v254
	v_fma_f32 v255, -v60, v133, v255
	ds_read_b128 v[122:125], v1 offset:22848
	ds_read_b32 v49, v1 offset:22880
	s_waitcnt lgkmcnt(2)
	v_fma_f32 v0, -v61, v220, v0
	v_fma_f32 v254, -v62, v221, v254
	v_fma_f32 v255, -v63, v222, v255
	v_fma_f32 v0, -v70, v223, v0
	s_waitcnt lgkmcnt(1)
	v_fma_f32 v254, -v68, v122, v254
	v_fma_f32 v255, -v69, v123, v255
	v_fma_f32 v0, -v66, v124, v0
	v_fma_f32 v254, -v67, v125, v254
	ds_read_b128 v[122:125], v1 offset:22864
	s_waitcnt lgkmcnt(0)
	v_fma_f32 v255, -v64, v122, v255
	v_fma_f32 v0, -v65, v123, v0
	v_fma_f32 v254, -v52, v124, v254
	v_fma_f32 v255, -v53, v125, v255
	v_fma_f32 v0, -v48, v49, v0
	v_add_f32_e32 v254, v0, v254
	v_add_f32_e32 v49, v254, v255
	ds_read_b128 v[122:125], v1 offset:23040
	ds_read_b128 v[126:129], v1 offset:23056
	ds_read_b128 v[130:133], v1 offset:23072
	ds_read_b128 v[220:223], v1 offset:23088
	s_waitcnt lgkmcnt(3)
	v_fma_f32 v0, -v2, v122, v46
	v_mul_f32_e64 v254, -v3, v123
	v_mul_f32_e64 v255, -v9, v124
	v_fma_f32 v0, -v50, v125, v0
	s_waitcnt lgkmcnt(2)
	v_fma_f32 v254, -v51, v126, v254
	v_fma_f32 v255, -v54, v127, v255
	v_fma_f32 v0, -v55, v128, v0
	v_fma_f32 v254, -v56, v129, v254
	s_waitcnt lgkmcnt(1)
	v_fma_f32 v255, -v57, v130, v255
	v_fma_f32 v0, -v58, v131, v0
	v_fma_f32 v254, -v59, v132, v254
	v_fma_f32 v255, -v60, v133, v255
	ds_read_b128 v[122:125], v1 offset:23104
	s_waitcnt lgkmcnt(1)
	v_fma_f32 v0, -v61, v220, v0
	v_fma_f32 v254, -v62, v221, v254
	v_fma_f32 v255, -v63, v222, v255
	v_fma_f32 v0, -v70, v223, v0
	s_waitcnt lgkmcnt(0)
	v_fma_f32 v254, -v68, v122, v254
	v_fma_f32 v255, -v69, v123, v255
	v_fma_f32 v0, -v66, v124, v0
	v_fma_f32 v254, -v67, v125, v254
	ds_read_b128 v[122:125], v1 offset:23120
	s_waitcnt lgkmcnt(0)
	v_fma_f32 v255, -v64, v122, v255
	v_fma_f32 v0, -v65, v123, v0
	ds_read_b64 v[122:123], v1 offset:23136
	v_fma_f32 v254, -v52, v124, v254
	v_fma_f32 v255, -v53, v125, v255
	s_waitcnt lgkmcnt(0)
	v_fma_f32 v0, -v48, v122, v0
	v_fma_f32 v254, -v49, v123, v254
	v_add_f32_e32 v254, v0, v254
	v_add_f32_e32 v46, v254, v255
	ds_read_b128 v[122:125], v1 offset:23296
	ds_read_b128 v[126:129], v1 offset:23312
	ds_read_b128 v[130:133], v1 offset:23328
	ds_read_b128 v[220:223], v1 offset:23344
	s_waitcnt lgkmcnt(3)
	v_fma_f32 v0, -v2, v122, v47
	v_mul_f32_e64 v254, -v3, v123
	v_mul_f32_e64 v255, -v9, v124
	v_fma_f32 v0, -v50, v125, v0
	s_waitcnt lgkmcnt(2)
	v_fma_f32 v254, -v51, v126, v254
	v_fma_f32 v255, -v54, v127, v255
	v_fma_f32 v0, -v55, v128, v0
	v_fma_f32 v254, -v56, v129, v254
	s_waitcnt lgkmcnt(1)
	v_fma_f32 v255, -v57, v130, v255
	v_fma_f32 v0, -v58, v131, v0
	v_fma_f32 v254, -v59, v132, v254
	v_fma_f32 v255, -v60, v133, v255
	ds_read_b128 v[122:125], v1 offset:23360
	s_waitcnt lgkmcnt(1)
	v_fma_f32 v0, -v61, v220, v0
	v_fma_f32 v254, -v62, v221, v254
	v_fma_f32 v255, -v63, v222, v255
	v_fma_f32 v0, -v70, v223, v0
	s_waitcnt lgkmcnt(0)
	v_fma_f32 v254, -v68, v122, v254
	v_fma_f32 v255, -v69, v123, v255
	v_fma_f32 v0, -v66, v124, v0
	v_fma_f32 v254, -v67, v125, v254
	ds_read_b128 v[122:125], v1 offset:23376
	s_waitcnt lgkmcnt(0)
	v_fma_f32 v255, -v64, v122, v255
	v_fma_f32 v0, -v65, v123, v0
	v_fma_f32 v254, -v52, v124, v254
	ds_read_b96 v[122:124], v1 offset:23392
	v_fma_f32 v255, -v53, v125, v255
	s_waitcnt lgkmcnt(0)
	v_fma_f32 v0, -v48, v122, v0
	v_fma_f32 v254, -v49, v123, v254
	v_fma_f32 v255, -v46, v124, v255
	v_add_f32_e32 v254, v0, v254
	v_add_f32_e32 v47, v254, v255
	ds_read_b128 v[122:125], v1 offset:23552
	ds_read_b128 v[126:129], v1 offset:23568
	ds_read_b128 v[130:133], v1 offset:23584
	ds_read_b128 v[220:223], v1 offset:23600
	s_waitcnt lgkmcnt(3)
	v_fma_f32 v0, -v2, v122, v44
	v_mul_f32_e64 v254, -v3, v123
	v_mul_f32_e64 v255, -v9, v124
	v_fma_f32 v0, -v50, v125, v0
	s_waitcnt lgkmcnt(2)
	v_fma_f32 v254, -v51, v126, v254
	v_fma_f32 v255, -v54, v127, v255
	v_fma_f32 v0, -v55, v128, v0
	v_fma_f32 v254, -v56, v129, v254
	s_waitcnt lgkmcnt(1)
	v_fma_f32 v255, -v57, v130, v255
	v_fma_f32 v0, -v58, v131, v0
	v_fma_f32 v254, -v59, v132, v254
	v_fma_f32 v255, -v60, v133, v255
	ds_read_b128 v[122:125], v1 offset:23616
	s_waitcnt lgkmcnt(1)
	v_fma_f32 v0, -v61, v220, v0
	v_fma_f32 v254, -v62, v221, v254
	v_fma_f32 v255, -v63, v222, v255
	v_fma_f32 v0, -v70, v223, v0
	s_waitcnt lgkmcnt(0)
	v_fma_f32 v254, -v68, v122, v254
	v_fma_f32 v255, -v69, v123, v255
	v_fma_f32 v0, -v66, v124, v0
	v_fma_f32 v254, -v67, v125, v254
	ds_read_b128 v[122:125], v1 offset:23632
	s_waitcnt lgkmcnt(0)
	v_fma_f32 v255, -v64, v122, v255
	v_fma_f32 v0, -v65, v123, v0
	v_fma_f32 v254, -v52, v124, v254
	v_fma_f32 v255, -v53, v125, v255
	ds_read_b128 v[122:125], v1 offset:23648
	s_waitcnt lgkmcnt(0)
	v_fma_f32 v0, -v48, v122, v0
	v_fma_f32 v254, -v49, v123, v254
	v_fma_f32 v255, -v46, v124, v255
	v_fma_f32 v0, -v47, v125, v0
	v_add_f32_e32 v254, v0, v254
	v_add_f32_e32 v44, v254, v255
	ds_read_b128 v[122:125], v1 offset:23808
	ds_read_b128 v[126:129], v1 offset:23824
	ds_read_b128 v[130:133], v1 offset:23840
	ds_read_b128 v[220:223], v1 offset:23856
	s_waitcnt lgkmcnt(3)
	v_fma_f32 v0, -v2, v122, v45
	v_mul_f32_e64 v254, -v3, v123
	v_mul_f32_e64 v255, -v9, v124
	v_fma_f32 v0, -v50, v125, v0
	s_waitcnt lgkmcnt(2)
	v_fma_f32 v254, -v51, v126, v254
	v_fma_f32 v255, -v54, v127, v255
	v_fma_f32 v0, -v55, v128, v0
	v_fma_f32 v254, -v56, v129, v254
	s_waitcnt lgkmcnt(1)
	v_fma_f32 v255, -v57, v130, v255
	v_fma_f32 v0, -v58, v131, v0
	v_fma_f32 v254, -v59, v132, v254
	v_fma_f32 v255, -v60, v133, v255
	ds_read_b128 v[122:125], v1 offset:23872
	ds_read_b32 v45, v1 offset:23920
	s_waitcnt lgkmcnt(2)
	v_fma_f32 v0, -v61, v220, v0
	v_fma_f32 v254, -v62, v221, v254
	v_fma_f32 v255, -v63, v222, v255
	v_fma_f32 v0, -v70, v223, v0
	s_waitcnt lgkmcnt(1)
	v_fma_f32 v254, -v68, v122, v254
	v_fma_f32 v255, -v69, v123, v255
	v_fma_f32 v0, -v66, v124, v0
	v_fma_f32 v254, -v67, v125, v254
	ds_read_b128 v[122:125], v1 offset:23888
	s_waitcnt lgkmcnt(0)
	v_fma_f32 v255, -v64, v122, v255
	v_fma_f32 v0, -v65, v123, v0
	v_fma_f32 v254, -v52, v124, v254
	v_fma_f32 v255, -v53, v125, v255
	ds_read_b128 v[122:125], v1 offset:23904
	s_waitcnt lgkmcnt(0)
	v_fma_f32 v0, -v48, v122, v0
	v_fma_f32 v254, -v49, v123, v254
	v_fma_f32 v255, -v46, v124, v255
	v_fma_f32 v0, -v47, v125, v0
	v_fma_f32 v254, -v44, v45, v254
	v_add_f32_e32 v254, v0, v254
	v_add_f32_e32 v45, v254, v255
	ds_read_b128 v[122:125], v1 offset:24064
	ds_read_b128 v[126:129], v1 offset:24080
	ds_read_b128 v[130:133], v1 offset:24096
	ds_read_b128 v[220:223], v1 offset:24112
	s_waitcnt lgkmcnt(3)
	v_fma_f32 v0, -v2, v122, v42
	v_mul_f32_e64 v254, -v3, v123
	v_mul_f32_e64 v255, -v9, v124
	v_fma_f32 v0, -v50, v125, v0
	s_waitcnt lgkmcnt(2)
	v_fma_f32 v254, -v51, v126, v254
	v_fma_f32 v255, -v54, v127, v255
	v_fma_f32 v0, -v55, v128, v0
	v_fma_f32 v254, -v56, v129, v254
	s_waitcnt lgkmcnt(1)
	v_fma_f32 v255, -v57, v130, v255
	v_fma_f32 v0, -v58, v131, v0
	v_fma_f32 v254, -v59, v132, v254
	v_fma_f32 v255, -v60, v133, v255
	ds_read_b128 v[122:125], v1 offset:24128
	s_waitcnt lgkmcnt(1)
	v_fma_f32 v0, -v61, v220, v0
	v_fma_f32 v254, -v62, v221, v254
	v_fma_f32 v255, -v63, v222, v255
	v_fma_f32 v0, -v70, v223, v0
	s_waitcnt lgkmcnt(0)
	v_fma_f32 v254, -v68, v122, v254
	v_fma_f32 v255, -v69, v123, v255
	v_fma_f32 v0, -v66, v124, v0
	v_fma_f32 v254, -v67, v125, v254
	ds_read_b128 v[122:125], v1 offset:24144
	s_waitcnt lgkmcnt(0)
	v_fma_f32 v255, -v64, v122, v255
	v_fma_f32 v0, -v65, v123, v0
	v_fma_f32 v254, -v52, v124, v254
	v_fma_f32 v255, -v53, v125, v255
	ds_read_b128 v[122:125], v1 offset:24160
	s_waitcnt lgkmcnt(0)
	v_fma_f32 v0, -v48, v122, v0
	v_fma_f32 v254, -v49, v123, v254
	ds_read_b64 v[122:123], v1 offset:24176
	v_fma_f32 v255, -v46, v124, v255
	v_fma_f32 v0, -v47, v125, v0
	s_waitcnt lgkmcnt(0)
	v_fma_f32 v254, -v44, v122, v254
	v_fma_f32 v255, -v45, v123, v255
	v_add_f32_e32 v254, v0, v254
	v_add_f32_e32 v42, v254, v255
	ds_read_b128 v[122:125], v1 offset:24320
	ds_read_b128 v[126:129], v1 offset:24336
	ds_read_b128 v[130:133], v1 offset:24352
	ds_read_b128 v[220:223], v1 offset:24368
	s_waitcnt lgkmcnt(3)
	v_fma_f32 v0, -v2, v122, v43
	v_mul_f32_e64 v254, -v3, v123
	v_mul_f32_e64 v255, -v9, v124
	v_fma_f32 v0, -v50, v125, v0
	s_waitcnt lgkmcnt(2)
	v_fma_f32 v254, -v51, v126, v254
	v_fma_f32 v255, -v54, v127, v255
	v_fma_f32 v0, -v55, v128, v0
	v_fma_f32 v254, -v56, v129, v254
	s_waitcnt lgkmcnt(1)
	v_fma_f32 v255, -v57, v130, v255
	v_fma_f32 v0, -v58, v131, v0
	v_fma_f32 v254, -v59, v132, v254
	v_fma_f32 v255, -v60, v133, v255
	ds_read_b128 v[122:125], v1 offset:24384
	s_waitcnt lgkmcnt(1)
	v_fma_f32 v0, -v61, v220, v0
	v_fma_f32 v254, -v62, v221, v254
	v_fma_f32 v255, -v63, v222, v255
	v_fma_f32 v0, -v70, v223, v0
	s_waitcnt lgkmcnt(0)
	v_fma_f32 v254, -v68, v122, v254
	v_fma_f32 v255, -v69, v123, v255
	v_fma_f32 v0, -v66, v124, v0
	v_fma_f32 v254, -v67, v125, v254
	ds_read_b128 v[122:125], v1 offset:24400
	s_waitcnt lgkmcnt(0)
	v_fma_f32 v255, -v64, v122, v255
	v_fma_f32 v0, -v65, v123, v0
	v_fma_f32 v254, -v52, v124, v254
	v_fma_f32 v255, -v53, v125, v255
	ds_read_b128 v[122:125], v1 offset:24416
	s_waitcnt lgkmcnt(0)
	v_fma_f32 v0, -v48, v122, v0
	v_fma_f32 v254, -v49, v123, v254
	v_fma_f32 v255, -v46, v124, v255
	ds_read_b96 v[122:124], v1 offset:24432
	v_fma_f32 v0, -v47, v125, v0
	s_waitcnt lgkmcnt(0)
	v_fma_f32 v254, -v44, v122, v254
	v_fma_f32 v255, -v45, v123, v255
	v_fma_f32 v0, -v42, v124, v0
	v_add_f32_e32 v254, v0, v254
	v_add_f32_e32 v43, v254, v255
	ds_read_b128 v[122:125], v1 offset:24576
	ds_read_b128 v[126:129], v1 offset:24592
	ds_read_b128 v[130:133], v1 offset:24608
	ds_read_b128 v[220:223], v1 offset:24624
	s_waitcnt lgkmcnt(3)
	v_fma_f32 v0, -v2, v122, v40
	v_mul_f32_e64 v254, -v3, v123
	v_mul_f32_e64 v255, -v9, v124
	v_fma_f32 v0, -v50, v125, v0
	s_waitcnt lgkmcnt(2)
	v_fma_f32 v254, -v51, v126, v254
	v_fma_f32 v255, -v54, v127, v255
	v_fma_f32 v0, -v55, v128, v0
	v_fma_f32 v254, -v56, v129, v254
	s_waitcnt lgkmcnt(1)
	v_fma_f32 v255, -v57, v130, v255
	v_fma_f32 v0, -v58, v131, v0
	v_fma_f32 v254, -v59, v132, v254
	v_fma_f32 v255, -v60, v133, v255
	ds_read_b128 v[122:125], v1 offset:24640
	s_waitcnt lgkmcnt(1)
	v_fma_f32 v0, -v61, v220, v0
	v_fma_f32 v254, -v62, v221, v254
	v_fma_f32 v255, -v63, v222, v255
	v_fma_f32 v0, -v70, v223, v0
	s_waitcnt lgkmcnt(0)
	v_fma_f32 v254, -v68, v122, v254
	v_fma_f32 v255, -v69, v123, v255
	v_fma_f32 v0, -v66, v124, v0
	v_fma_f32 v254, -v67, v125, v254
	ds_read_b128 v[122:125], v1 offset:24656
	s_waitcnt lgkmcnt(0)
	v_fma_f32 v255, -v64, v122, v255
	v_fma_f32 v0, -v65, v123, v0
	v_fma_f32 v254, -v52, v124, v254
	v_fma_f32 v255, -v53, v125, v255
	ds_read_b128 v[122:125], v1 offset:24672
	s_waitcnt lgkmcnt(0)
	v_fma_f32 v0, -v48, v122, v0
	v_fma_f32 v254, -v49, v123, v254
	v_fma_f32 v255, -v46, v124, v255
	v_fma_f32 v0, -v47, v125, v0
	ds_read_b128 v[122:125], v1 offset:24688
	s_waitcnt lgkmcnt(0)
	v_fma_f32 v254, -v44, v122, v254
	v_fma_f32 v255, -v45, v123, v255
	v_fma_f32 v0, -v42, v124, v0
	v_fma_f32 v254, -v43, v125, v254
	v_add_f32_e32 v254, v0, v254
	v_add_f32_e32 v40, v254, v255
	ds_read_b128 v[122:125], v1 offset:24832
	ds_read_b128 v[126:129], v1 offset:24848
	ds_read_b128 v[130:133], v1 offset:24864
	ds_read_b128 v[220:223], v1 offset:24880
	s_waitcnt lgkmcnt(3)
	v_fma_f32 v0, -v2, v122, v41
	v_mul_f32_e64 v254, -v3, v123
	v_mul_f32_e64 v255, -v9, v124
	v_fma_f32 v0, -v50, v125, v0
	s_waitcnt lgkmcnt(2)
	v_fma_f32 v254, -v51, v126, v254
	v_fma_f32 v255, -v54, v127, v255
	v_fma_f32 v0, -v55, v128, v0
	v_fma_f32 v254, -v56, v129, v254
	s_waitcnt lgkmcnt(1)
	v_fma_f32 v255, -v57, v130, v255
	v_fma_f32 v0, -v58, v131, v0
	v_fma_f32 v254, -v59, v132, v254
	v_fma_f32 v255, -v60, v133, v255
	ds_read_b128 v[122:125], v1 offset:24896
	ds_read_b32 v41, v1 offset:24960
	s_waitcnt lgkmcnt(2)
	v_fma_f32 v0, -v61, v220, v0
	v_fma_f32 v254, -v62, v221, v254
	v_fma_f32 v255, -v63, v222, v255
	v_fma_f32 v0, -v70, v223, v0
	s_waitcnt lgkmcnt(1)
	v_fma_f32 v254, -v68, v122, v254
	v_fma_f32 v255, -v69, v123, v255
	v_fma_f32 v0, -v66, v124, v0
	v_fma_f32 v254, -v67, v125, v254
	ds_read_b128 v[122:125], v1 offset:24912
	s_waitcnt lgkmcnt(0)
	v_fma_f32 v255, -v64, v122, v255
	v_fma_f32 v0, -v65, v123, v0
	v_fma_f32 v254, -v52, v124, v254
	v_fma_f32 v255, -v53, v125, v255
	ds_read_b128 v[122:125], v1 offset:24928
	s_waitcnt lgkmcnt(0)
	v_fma_f32 v0, -v48, v122, v0
	v_fma_f32 v254, -v49, v123, v254
	v_fma_f32 v255, -v46, v124, v255
	v_fma_f32 v0, -v47, v125, v0
	ds_read_b128 v[122:125], v1 offset:24944
	s_waitcnt lgkmcnt(0)
	v_fma_f32 v254, -v44, v122, v254
	v_fma_f32 v255, -v45, v123, v255
	v_fma_f32 v0, -v42, v124, v0
	v_fma_f32 v254, -v43, v125, v254
	v_fma_f32 v255, -v40, v41, v255
	v_add_f32_e32 v254, v0, v254
	v_add_f32_e32 v41, v254, v255
	ds_read_b128 v[122:125], v1 offset:25088
	ds_read_b128 v[126:129], v1 offset:25104
	ds_read_b128 v[130:133], v1 offset:25120
	ds_read_b128 v[220:223], v1 offset:25136
	s_waitcnt lgkmcnt(3)
	v_fma_f32 v0, -v2, v122, v38
	v_mul_f32_e64 v254, -v3, v123
	v_mul_f32_e64 v255, -v9, v124
	v_fma_f32 v0, -v50, v125, v0
	s_waitcnt lgkmcnt(2)
	v_fma_f32 v254, -v51, v126, v254
	v_fma_f32 v255, -v54, v127, v255
	v_fma_f32 v0, -v55, v128, v0
	v_fma_f32 v254, -v56, v129, v254
	s_waitcnt lgkmcnt(1)
	v_fma_f32 v255, -v57, v130, v255
	v_fma_f32 v0, -v58, v131, v0
	v_fma_f32 v254, -v59, v132, v254
	v_fma_f32 v255, -v60, v133, v255
	ds_read_b128 v[122:125], v1 offset:25152
	s_waitcnt lgkmcnt(1)
	v_fma_f32 v0, -v61, v220, v0
	v_fma_f32 v254, -v62, v221, v254
	v_fma_f32 v255, -v63, v222, v255
	v_fma_f32 v0, -v70, v223, v0
	s_waitcnt lgkmcnt(0)
	v_fma_f32 v254, -v68, v122, v254
	v_fma_f32 v255, -v69, v123, v255
	v_fma_f32 v0, -v66, v124, v0
	v_fma_f32 v254, -v67, v125, v254
	ds_read_b128 v[122:125], v1 offset:25168
	s_waitcnt lgkmcnt(0)
	v_fma_f32 v255, -v64, v122, v255
	v_fma_f32 v0, -v65, v123, v0
	v_fma_f32 v254, -v52, v124, v254
	v_fma_f32 v255, -v53, v125, v255
	ds_read_b128 v[122:125], v1 offset:25184
	s_waitcnt lgkmcnt(0)
	v_fma_f32 v0, -v48, v122, v0
	v_fma_f32 v254, -v49, v123, v254
	v_fma_f32 v255, -v46, v124, v255
	v_fma_f32 v0, -v47, v125, v0
	ds_read_b128 v[122:125], v1 offset:25200
	s_waitcnt lgkmcnt(0)
	v_fma_f32 v254, -v44, v122, v254
	v_fma_f32 v255, -v45, v123, v255
	ds_read_b64 v[122:123], v1 offset:25216
	v_fma_f32 v0, -v42, v124, v0
	v_fma_f32 v254, -v43, v125, v254
	s_waitcnt lgkmcnt(0)
	v_fma_f32 v255, -v40, v122, v255
	v_fma_f32 v0, -v41, v123, v0
	v_add_f32_e32 v254, v0, v254
	v_add_f32_e32 v38, v254, v255
	ds_read_b128 v[122:125], v1 offset:25344
	ds_read_b128 v[126:129], v1 offset:25360
	ds_read_b128 v[130:133], v1 offset:25376
	ds_read_b128 v[220:223], v1 offset:25392
	s_waitcnt lgkmcnt(3)
	v_fma_f32 v0, -v2, v122, v39
	v_mul_f32_e64 v254, -v3, v123
	v_mul_f32_e64 v255, -v9, v124
	v_fma_f32 v0, -v50, v125, v0
	s_waitcnt lgkmcnt(2)
	v_fma_f32 v254, -v51, v126, v254
	v_fma_f32 v255, -v54, v127, v255
	v_fma_f32 v0, -v55, v128, v0
	v_fma_f32 v254, -v56, v129, v254
	s_waitcnt lgkmcnt(1)
	v_fma_f32 v255, -v57, v130, v255
	v_fma_f32 v0, -v58, v131, v0
	v_fma_f32 v254, -v59, v132, v254
	v_fma_f32 v255, -v60, v133, v255
	ds_read_b128 v[122:125], v1 offset:25408
	s_waitcnt lgkmcnt(1)
	v_fma_f32 v0, -v61, v220, v0
	v_fma_f32 v254, -v62, v221, v254
	v_fma_f32 v255, -v63, v222, v255
	v_fma_f32 v0, -v70, v223, v0
	s_waitcnt lgkmcnt(0)
	v_fma_f32 v254, -v68, v122, v254
	v_fma_f32 v255, -v69, v123, v255
	v_fma_f32 v0, -v66, v124, v0
	v_fma_f32 v254, -v67, v125, v254
	ds_read_b128 v[122:125], v1 offset:25424
	s_waitcnt lgkmcnt(0)
	v_fma_f32 v255, -v64, v122, v255
	v_fma_f32 v0, -v65, v123, v0
	v_fma_f32 v254, -v52, v124, v254
	v_fma_f32 v255, -v53, v125, v255
	ds_read_b128 v[122:125], v1 offset:25440
	s_waitcnt lgkmcnt(0)
	v_fma_f32 v0, -v48, v122, v0
	v_fma_f32 v254, -v49, v123, v254
	v_fma_f32 v255, -v46, v124, v255
	v_fma_f32 v0, -v47, v125, v0
	ds_read_b128 v[122:125], v1 offset:25456
	s_waitcnt lgkmcnt(0)
	v_fma_f32 v254, -v44, v122, v254
	v_fma_f32 v255, -v45, v123, v255
	v_fma_f32 v0, -v42, v124, v0
	ds_read_b96 v[122:124], v1 offset:25472
	v_fma_f32 v254, -v43, v125, v254
	s_waitcnt lgkmcnt(0)
	v_fma_f32 v255, -v40, v122, v255
	v_fma_f32 v0, -v41, v123, v0
	v_fma_f32 v254, -v38, v124, v254
	v_add_f32_e32 v254, v0, v254
	v_add_f32_e32 v39, v254, v255
	ds_read_b128 v[122:125], v1 offset:25600
	ds_read_b128 v[126:129], v1 offset:25616
	ds_read_b128 v[130:133], v1 offset:25632
	ds_read_b128 v[220:223], v1 offset:25648
	s_waitcnt lgkmcnt(3)
	v_fma_f32 v0, -v2, v122, v36
	v_mul_f32_e64 v254, -v3, v123
	v_mul_f32_e64 v255, -v9, v124
	v_fma_f32 v0, -v50, v125, v0
	s_waitcnt lgkmcnt(2)
	v_fma_f32 v254, -v51, v126, v254
	v_fma_f32 v255, -v54, v127, v255
	v_fma_f32 v0, -v55, v128, v0
	v_fma_f32 v254, -v56, v129, v254
	s_waitcnt lgkmcnt(1)
	v_fma_f32 v255, -v57, v130, v255
	v_fma_f32 v0, -v58, v131, v0
	v_fma_f32 v254, -v59, v132, v254
	v_fma_f32 v255, -v60, v133, v255
	ds_read_b128 v[122:125], v1 offset:25664
	s_waitcnt lgkmcnt(1)
	v_fma_f32 v0, -v61, v220, v0
	v_fma_f32 v254, -v62, v221, v254
	v_fma_f32 v255, -v63, v222, v255
	v_fma_f32 v0, -v70, v223, v0
	s_waitcnt lgkmcnt(0)
	v_fma_f32 v254, -v68, v122, v254
	v_fma_f32 v255, -v69, v123, v255
	v_fma_f32 v0, -v66, v124, v0
	v_fma_f32 v254, -v67, v125, v254
	ds_read_b128 v[122:125], v1 offset:25680
	s_waitcnt lgkmcnt(0)
	v_fma_f32 v255, -v64, v122, v255
	v_fma_f32 v0, -v65, v123, v0
	v_fma_f32 v254, -v52, v124, v254
	v_fma_f32 v255, -v53, v125, v255
	ds_read_b128 v[122:125], v1 offset:25696
	s_waitcnt lgkmcnt(0)
	v_fma_f32 v0, -v48, v122, v0
	v_fma_f32 v254, -v49, v123, v254
	v_fma_f32 v255, -v46, v124, v255
	v_fma_f32 v0, -v47, v125, v0
	ds_read_b128 v[122:125], v1 offset:25712
	s_waitcnt lgkmcnt(0)
	v_fma_f32 v254, -v44, v122, v254
	v_fma_f32 v255, -v45, v123, v255
	v_fma_f32 v0, -v42, v124, v0
	v_fma_f32 v254, -v43, v125, v254
	ds_read_b128 v[122:125], v1 offset:25728
	s_waitcnt lgkmcnt(0)
	v_fma_f32 v255, -v40, v122, v255
	v_fma_f32 v0, -v41, v123, v0
	v_fma_f32 v254, -v38, v124, v254
	v_fma_f32 v255, -v39, v125, v255
	v_add_f32_e32 v254, v0, v254
	v_add_f32_e32 v36, v254, v255
	ds_read_b128 v[122:125], v1 offset:25856
	ds_read_b128 v[126:129], v1 offset:25872
	ds_read_b128 v[130:133], v1 offset:25888
	ds_read_b128 v[220:223], v1 offset:25904
	s_waitcnt lgkmcnt(3)
	v_fma_f32 v0, -v2, v122, v37
	v_mul_f32_e64 v254, -v3, v123
	v_mul_f32_e64 v255, -v9, v124
	v_fma_f32 v0, -v50, v125, v0
	s_waitcnt lgkmcnt(2)
	v_fma_f32 v254, -v51, v126, v254
	v_fma_f32 v255, -v54, v127, v255
	v_fma_f32 v0, -v55, v128, v0
	v_fma_f32 v254, -v56, v129, v254
	s_waitcnt lgkmcnt(1)
	v_fma_f32 v255, -v57, v130, v255
	v_fma_f32 v0, -v58, v131, v0
	v_fma_f32 v254, -v59, v132, v254
	v_fma_f32 v255, -v60, v133, v255
	ds_read_b128 v[122:125], v1 offset:25920
	ds_read_b32 v37, v1 offset:26000
	s_waitcnt lgkmcnt(2)
	v_fma_f32 v0, -v61, v220, v0
	v_fma_f32 v254, -v62, v221, v254
	v_fma_f32 v255, -v63, v222, v255
	v_fma_f32 v0, -v70, v223, v0
	s_waitcnt lgkmcnt(1)
	v_fma_f32 v254, -v68, v122, v254
	v_fma_f32 v255, -v69, v123, v255
	v_fma_f32 v0, -v66, v124, v0
	v_fma_f32 v254, -v67, v125, v254
	ds_read_b128 v[122:125], v1 offset:25936
	s_waitcnt lgkmcnt(0)
	v_fma_f32 v255, -v64, v122, v255
	v_fma_f32 v0, -v65, v123, v0
	v_fma_f32 v254, -v52, v124, v254
	v_fma_f32 v255, -v53, v125, v255
	ds_read_b128 v[122:125], v1 offset:25952
	s_waitcnt lgkmcnt(0)
	v_fma_f32 v0, -v48, v122, v0
	v_fma_f32 v254, -v49, v123, v254
	v_fma_f32 v255, -v46, v124, v255
	v_fma_f32 v0, -v47, v125, v0
	ds_read_b128 v[122:125], v1 offset:25968
	s_waitcnt lgkmcnt(0)
	v_fma_f32 v254, -v44, v122, v254
	v_fma_f32 v255, -v45, v123, v255
	v_fma_f32 v0, -v42, v124, v0
	v_fma_f32 v254, -v43, v125, v254
	ds_read_b128 v[122:125], v1 offset:25984
	s_waitcnt lgkmcnt(0)
	v_fma_f32 v255, -v40, v122, v255
	v_fma_f32 v0, -v41, v123, v0
	v_fma_f32 v254, -v38, v124, v254
	v_fma_f32 v255, -v39, v125, v255
	v_fma_f32 v0, -v36, v37, v0
	v_add_f32_e32 v254, v0, v254
	v_add_f32_e32 v37, v254, v255
	ds_read_b128 v[122:125], v1 offset:26112
	ds_read_b128 v[126:129], v1 offset:26128
	ds_read_b128 v[130:133], v1 offset:26144
	ds_read_b128 v[220:223], v1 offset:26160
	s_waitcnt lgkmcnt(3)
	v_fma_f32 v0, -v2, v122, v34
	v_mul_f32_e64 v254, -v3, v123
	v_mul_f32_e64 v255, -v9, v124
	v_fma_f32 v0, -v50, v125, v0
	s_waitcnt lgkmcnt(2)
	v_fma_f32 v254, -v51, v126, v254
	v_fma_f32 v255, -v54, v127, v255
	v_fma_f32 v0, -v55, v128, v0
	v_fma_f32 v254, -v56, v129, v254
	s_waitcnt lgkmcnt(1)
	v_fma_f32 v255, -v57, v130, v255
	v_fma_f32 v0, -v58, v131, v0
	v_fma_f32 v254, -v59, v132, v254
	v_fma_f32 v255, -v60, v133, v255
	ds_read_b128 v[122:125], v1 offset:26176
	s_waitcnt lgkmcnt(1)
	v_fma_f32 v0, -v61, v220, v0
	v_fma_f32 v254, -v62, v221, v254
	v_fma_f32 v255, -v63, v222, v255
	v_fma_f32 v0, -v70, v223, v0
	s_waitcnt lgkmcnt(0)
	v_fma_f32 v254, -v68, v122, v254
	v_fma_f32 v255, -v69, v123, v255
	v_fma_f32 v0, -v66, v124, v0
	v_fma_f32 v254, -v67, v125, v254
	ds_read_b128 v[122:125], v1 offset:26192
	s_waitcnt lgkmcnt(0)
	v_fma_f32 v255, -v64, v122, v255
	v_fma_f32 v0, -v65, v123, v0
	v_fma_f32 v254, -v52, v124, v254
	v_fma_f32 v255, -v53, v125, v255
	ds_read_b128 v[122:125], v1 offset:26208
	s_waitcnt lgkmcnt(0)
	v_fma_f32 v0, -v48, v122, v0
	v_fma_f32 v254, -v49, v123, v254
	v_fma_f32 v255, -v46, v124, v255
	v_fma_f32 v0, -v47, v125, v0
	ds_read_b128 v[122:125], v1 offset:26224
	s_waitcnt lgkmcnt(0)
	v_fma_f32 v254, -v44, v122, v254
	v_fma_f32 v255, -v45, v123, v255
	v_fma_f32 v0, -v42, v124, v0
	v_fma_f32 v254, -v43, v125, v254
	ds_read_b128 v[122:125], v1 offset:26240
	s_waitcnt lgkmcnt(0)
	v_fma_f32 v255, -v40, v122, v255
	v_fma_f32 v0, -v41, v123, v0
	ds_read_b64 v[122:123], v1 offset:26256
	v_fma_f32 v254, -v38, v124, v254
	v_fma_f32 v255, -v39, v125, v255
	s_waitcnt lgkmcnt(0)
	v_fma_f32 v0, -v36, v122, v0
	v_fma_f32 v254, -v37, v123, v254
	v_add_f32_e32 v254, v0, v254
	v_add_f32_e32 v34, v254, v255
	ds_read_b128 v[122:125], v1 offset:26368
	ds_read_b128 v[126:129], v1 offset:26384
	ds_read_b128 v[130:133], v1 offset:26400
	ds_read_b128 v[220:223], v1 offset:26416
	s_waitcnt lgkmcnt(3)
	v_fma_f32 v0, -v2, v122, v35
	v_mul_f32_e64 v254, -v3, v123
	v_mul_f32_e64 v255, -v9, v124
	v_fma_f32 v0, -v50, v125, v0
	s_waitcnt lgkmcnt(2)
	v_fma_f32 v254, -v51, v126, v254
	v_fma_f32 v255, -v54, v127, v255
	v_fma_f32 v0, -v55, v128, v0
	v_fma_f32 v254, -v56, v129, v254
	s_waitcnt lgkmcnt(1)
	v_fma_f32 v255, -v57, v130, v255
	v_fma_f32 v0, -v58, v131, v0
	v_fma_f32 v254, -v59, v132, v254
	v_fma_f32 v255, -v60, v133, v255
	ds_read_b128 v[122:125], v1 offset:26432
	s_waitcnt lgkmcnt(1)
	v_fma_f32 v0, -v61, v220, v0
	v_fma_f32 v254, -v62, v221, v254
	v_fma_f32 v255, -v63, v222, v255
	v_fma_f32 v0, -v70, v223, v0
	s_waitcnt lgkmcnt(0)
	v_fma_f32 v254, -v68, v122, v254
	v_fma_f32 v255, -v69, v123, v255
	v_fma_f32 v0, -v66, v124, v0
	v_fma_f32 v254, -v67, v125, v254
	ds_read_b128 v[122:125], v1 offset:26448
	s_waitcnt lgkmcnt(0)
	v_fma_f32 v255, -v64, v122, v255
	v_fma_f32 v0, -v65, v123, v0
	v_fma_f32 v254, -v52, v124, v254
	v_fma_f32 v255, -v53, v125, v255
	ds_read_b128 v[122:125], v1 offset:26464
	s_waitcnt lgkmcnt(0)
	v_fma_f32 v0, -v48, v122, v0
	v_fma_f32 v254, -v49, v123, v254
	v_fma_f32 v255, -v46, v124, v255
	v_fma_f32 v0, -v47, v125, v0
	ds_read_b128 v[122:125], v1 offset:26480
	s_waitcnt lgkmcnt(0)
	v_fma_f32 v254, -v44, v122, v254
	v_fma_f32 v255, -v45, v123, v255
	v_fma_f32 v0, -v42, v124, v0
	v_fma_f32 v254, -v43, v125, v254
	ds_read_b128 v[122:125], v1 offset:26496
	s_waitcnt lgkmcnt(0)
	v_fma_f32 v255, -v40, v122, v255
	v_fma_f32 v0, -v41, v123, v0
	v_fma_f32 v254, -v38, v124, v254
	ds_read_b96 v[122:124], v1 offset:26512
	v_fma_f32 v255, -v39, v125, v255
	s_waitcnt lgkmcnt(0)
	v_fma_f32 v0, -v36, v122, v0
	v_fma_f32 v254, -v37, v123, v254
	v_fma_f32 v255, -v34, v124, v255
	v_add_f32_e32 v254, v0, v254
	v_add_f32_e32 v35, v254, v255
	ds_read_b128 v[122:125], v1 offset:26624
	ds_read_b128 v[126:129], v1 offset:26640
	ds_read_b128 v[130:133], v1 offset:26656
	ds_read_b128 v[220:223], v1 offset:26672
	s_waitcnt lgkmcnt(3)
	v_fma_f32 v0, -v2, v122, v32
	v_mul_f32_e64 v254, -v3, v123
	v_mul_f32_e64 v255, -v9, v124
	v_fma_f32 v0, -v50, v125, v0
	s_waitcnt lgkmcnt(2)
	v_fma_f32 v254, -v51, v126, v254
	v_fma_f32 v255, -v54, v127, v255
	v_fma_f32 v0, -v55, v128, v0
	v_fma_f32 v254, -v56, v129, v254
	s_waitcnt lgkmcnt(1)
	v_fma_f32 v255, -v57, v130, v255
	v_fma_f32 v0, -v58, v131, v0
	v_fma_f32 v254, -v59, v132, v254
	v_fma_f32 v255, -v60, v133, v255
	ds_read_b128 v[122:125], v1 offset:26688
	s_waitcnt lgkmcnt(1)
	v_fma_f32 v0, -v61, v220, v0
	v_fma_f32 v254, -v62, v221, v254
	v_fma_f32 v255, -v63, v222, v255
	v_fma_f32 v0, -v70, v223, v0
	s_waitcnt lgkmcnt(0)
	v_fma_f32 v254, -v68, v122, v254
	v_fma_f32 v255, -v69, v123, v255
	v_fma_f32 v0, -v66, v124, v0
	v_fma_f32 v254, -v67, v125, v254
	ds_read_b128 v[122:125], v1 offset:26704
	s_waitcnt lgkmcnt(0)
	v_fma_f32 v255, -v64, v122, v255
	v_fma_f32 v0, -v65, v123, v0
	v_fma_f32 v254, -v52, v124, v254
	v_fma_f32 v255, -v53, v125, v255
	ds_read_b128 v[122:125], v1 offset:26720
	s_waitcnt lgkmcnt(0)
	v_fma_f32 v0, -v48, v122, v0
	v_fma_f32 v254, -v49, v123, v254
	v_fma_f32 v255, -v46, v124, v255
	v_fma_f32 v0, -v47, v125, v0
	ds_read_b128 v[122:125], v1 offset:26736
	s_waitcnt lgkmcnt(0)
	v_fma_f32 v254, -v44, v122, v254
	v_fma_f32 v255, -v45, v123, v255
	v_fma_f32 v0, -v42, v124, v0
	v_fma_f32 v254, -v43, v125, v254
	ds_read_b128 v[122:125], v1 offset:26752
	s_waitcnt lgkmcnt(0)
	v_fma_f32 v255, -v40, v122, v255
	v_fma_f32 v0, -v41, v123, v0
	v_fma_f32 v254, -v38, v124, v254
	v_fma_f32 v255, -v39, v125, v255
	ds_read_b128 v[122:125], v1 offset:26768
	s_waitcnt lgkmcnt(0)
	v_fma_f32 v0, -v36, v122, v0
	v_fma_f32 v254, -v37, v123, v254
	v_fma_f32 v255, -v34, v124, v255
	v_fma_f32 v0, -v35, v125, v0
	v_add_f32_e32 v254, v0, v254
	v_add_f32_e32 v32, v254, v255
	ds_read_b128 v[122:125], v1 offset:26880
	ds_read_b128 v[126:129], v1 offset:26896
	ds_read_b128 v[130:133], v1 offset:26912
	ds_read_b128 v[220:223], v1 offset:26928
	s_waitcnt lgkmcnt(3)
	v_fma_f32 v0, -v2, v122, v33
	v_mul_f32_e64 v254, -v3, v123
	v_mul_f32_e64 v255, -v9, v124
	v_fma_f32 v0, -v50, v125, v0
	s_waitcnt lgkmcnt(2)
	v_fma_f32 v254, -v51, v126, v254
	v_fma_f32 v255, -v54, v127, v255
	v_fma_f32 v0, -v55, v128, v0
	v_fma_f32 v254, -v56, v129, v254
	s_waitcnt lgkmcnt(1)
	v_fma_f32 v255, -v57, v130, v255
	v_fma_f32 v0, -v58, v131, v0
	v_fma_f32 v254, -v59, v132, v254
	v_fma_f32 v255, -v60, v133, v255
	ds_read_b128 v[122:125], v1 offset:26944
	ds_read_b32 v33, v1 offset:27040
	s_waitcnt lgkmcnt(2)
	v_fma_f32 v0, -v61, v220, v0
	v_fma_f32 v254, -v62, v221, v254
	v_fma_f32 v255, -v63, v222, v255
	v_fma_f32 v0, -v70, v223, v0
	s_waitcnt lgkmcnt(1)
	v_fma_f32 v254, -v68, v122, v254
	v_fma_f32 v255, -v69, v123, v255
	v_fma_f32 v0, -v66, v124, v0
	v_fma_f32 v254, -v67, v125, v254
	ds_read_b128 v[122:125], v1 offset:26960
	s_waitcnt lgkmcnt(0)
	v_fma_f32 v255, -v64, v122, v255
	v_fma_f32 v0, -v65, v123, v0
	v_fma_f32 v254, -v52, v124, v254
	v_fma_f32 v255, -v53, v125, v255
	ds_read_b128 v[122:125], v1 offset:26976
	s_waitcnt lgkmcnt(0)
	v_fma_f32 v0, -v48, v122, v0
	v_fma_f32 v254, -v49, v123, v254
	v_fma_f32 v255, -v46, v124, v255
	v_fma_f32 v0, -v47, v125, v0
	ds_read_b128 v[122:125], v1 offset:26992
	s_waitcnt lgkmcnt(0)
	v_fma_f32 v254, -v44, v122, v254
	v_fma_f32 v255, -v45, v123, v255
	v_fma_f32 v0, -v42, v124, v0
	v_fma_f32 v254, -v43, v125, v254
	ds_read_b128 v[122:125], v1 offset:27008
	s_waitcnt lgkmcnt(0)
	v_fma_f32 v255, -v40, v122, v255
	v_fma_f32 v0, -v41, v123, v0
	v_fma_f32 v254, -v38, v124, v254
	v_fma_f32 v255, -v39, v125, v255
	ds_read_b128 v[122:125], v1 offset:27024
	s_waitcnt lgkmcnt(0)
	v_fma_f32 v0, -v36, v122, v0
	v_fma_f32 v254, -v37, v123, v254
	v_fma_f32 v255, -v34, v124, v255
	v_fma_f32 v0, -v35, v125, v0
	v_fma_f32 v254, -v32, v33, v254
	v_add_f32_e32 v254, v0, v254
	v_add_f32_e32 v33, v254, v255
	ds_read_b128 v[122:125], v1 offset:27136
	ds_read_b128 v[126:129], v1 offset:27152
	ds_read_b128 v[130:133], v1 offset:27168
	ds_read_b128 v[220:223], v1 offset:27184
	s_waitcnt lgkmcnt(3)
	v_fma_f32 v0, -v2, v122, v30
	v_mul_f32_e64 v254, -v3, v123
	v_mul_f32_e64 v255, -v9, v124
	v_fma_f32 v0, -v50, v125, v0
	s_waitcnt lgkmcnt(2)
	v_fma_f32 v254, -v51, v126, v254
	v_fma_f32 v255, -v54, v127, v255
	v_fma_f32 v0, -v55, v128, v0
	v_fma_f32 v254, -v56, v129, v254
	s_waitcnt lgkmcnt(1)
	v_fma_f32 v255, -v57, v130, v255
	v_fma_f32 v0, -v58, v131, v0
	v_fma_f32 v254, -v59, v132, v254
	v_fma_f32 v255, -v60, v133, v255
	ds_read_b128 v[122:125], v1 offset:27200
	s_waitcnt lgkmcnt(1)
	v_fma_f32 v0, -v61, v220, v0
	v_fma_f32 v254, -v62, v221, v254
	v_fma_f32 v255, -v63, v222, v255
	v_fma_f32 v0, -v70, v223, v0
	s_waitcnt lgkmcnt(0)
	v_fma_f32 v254, -v68, v122, v254
	v_fma_f32 v255, -v69, v123, v255
	v_fma_f32 v0, -v66, v124, v0
	v_fma_f32 v254, -v67, v125, v254
	ds_read_b128 v[122:125], v1 offset:27216
	s_waitcnt lgkmcnt(0)
	v_fma_f32 v255, -v64, v122, v255
	v_fma_f32 v0, -v65, v123, v0
	v_fma_f32 v254, -v52, v124, v254
	v_fma_f32 v255, -v53, v125, v255
	ds_read_b128 v[122:125], v1 offset:27232
	s_waitcnt lgkmcnt(0)
	v_fma_f32 v0, -v48, v122, v0
	v_fma_f32 v254, -v49, v123, v254
	v_fma_f32 v255, -v46, v124, v255
	v_fma_f32 v0, -v47, v125, v0
	ds_read_b128 v[122:125], v1 offset:27248
	s_waitcnt lgkmcnt(0)
	v_fma_f32 v254, -v44, v122, v254
	v_fma_f32 v255, -v45, v123, v255
	v_fma_f32 v0, -v42, v124, v0
	v_fma_f32 v254, -v43, v125, v254
	ds_read_b128 v[122:125], v1 offset:27264
	s_waitcnt lgkmcnt(0)
	v_fma_f32 v255, -v40, v122, v255
	v_fma_f32 v0, -v41, v123, v0
	v_fma_f32 v254, -v38, v124, v254
	v_fma_f32 v255, -v39, v125, v255
	ds_read_b128 v[122:125], v1 offset:27280
	s_waitcnt lgkmcnt(0)
	v_fma_f32 v0, -v36, v122, v0
	v_fma_f32 v254, -v37, v123, v254
	ds_read_b64 v[122:123], v1 offset:27296
	v_fma_f32 v255, -v34, v124, v255
	v_fma_f32 v0, -v35, v125, v0
	s_waitcnt lgkmcnt(0)
	v_fma_f32 v254, -v32, v122, v254
	v_fma_f32 v255, -v33, v123, v255
	v_add_f32_e32 v254, v0, v254
	v_add_f32_e32 v30, v254, v255
	ds_read_b128 v[122:125], v1 offset:27392
	ds_read_b128 v[126:129], v1 offset:27408
	ds_read_b128 v[130:133], v1 offset:27424
	ds_read_b128 v[220:223], v1 offset:27440
	s_waitcnt lgkmcnt(3)
	v_fma_f32 v0, -v2, v122, v31
	v_mul_f32_e64 v254, -v3, v123
	v_mul_f32_e64 v255, -v9, v124
	v_fma_f32 v0, -v50, v125, v0
	s_waitcnt lgkmcnt(2)
	v_fma_f32 v254, -v51, v126, v254
	v_fma_f32 v255, -v54, v127, v255
	v_fma_f32 v0, -v55, v128, v0
	v_fma_f32 v254, -v56, v129, v254
	s_waitcnt lgkmcnt(1)
	v_fma_f32 v255, -v57, v130, v255
	v_fma_f32 v0, -v58, v131, v0
	v_fma_f32 v254, -v59, v132, v254
	v_fma_f32 v255, -v60, v133, v255
	ds_read_b128 v[122:125], v1 offset:27456
	s_waitcnt lgkmcnt(1)
	v_fma_f32 v0, -v61, v220, v0
	v_fma_f32 v254, -v62, v221, v254
	v_fma_f32 v255, -v63, v222, v255
	v_fma_f32 v0, -v70, v223, v0
	s_waitcnt lgkmcnt(0)
	v_fma_f32 v254, -v68, v122, v254
	v_fma_f32 v255, -v69, v123, v255
	v_fma_f32 v0, -v66, v124, v0
	v_fma_f32 v254, -v67, v125, v254
	ds_read_b128 v[122:125], v1 offset:27472
	s_waitcnt lgkmcnt(0)
	v_fma_f32 v255, -v64, v122, v255
	v_fma_f32 v0, -v65, v123, v0
	v_fma_f32 v254, -v52, v124, v254
	v_fma_f32 v255, -v53, v125, v255
	ds_read_b128 v[122:125], v1 offset:27488
	s_waitcnt lgkmcnt(0)
	v_fma_f32 v0, -v48, v122, v0
	v_fma_f32 v254, -v49, v123, v254
	v_fma_f32 v255, -v46, v124, v255
	v_fma_f32 v0, -v47, v125, v0
	ds_read_b128 v[122:125], v1 offset:27504
	s_waitcnt lgkmcnt(0)
	v_fma_f32 v254, -v44, v122, v254
	v_fma_f32 v255, -v45, v123, v255
	v_fma_f32 v0, -v42, v124, v0
	v_fma_f32 v254, -v43, v125, v254
	ds_read_b128 v[122:125], v1 offset:27520
	s_waitcnt lgkmcnt(0)
	v_fma_f32 v255, -v40, v122, v255
	v_fma_f32 v0, -v41, v123, v0
	v_fma_f32 v254, -v38, v124, v254
	v_fma_f32 v255, -v39, v125, v255
	ds_read_b128 v[122:125], v1 offset:27536
	s_waitcnt lgkmcnt(0)
	v_fma_f32 v0, -v36, v122, v0
	v_fma_f32 v254, -v37, v123, v254
	v_fma_f32 v255, -v34, v124, v255
	ds_read_b96 v[122:124], v1 offset:27552
	v_fma_f32 v0, -v35, v125, v0
	s_waitcnt lgkmcnt(0)
	v_fma_f32 v254, -v32, v122, v254
	v_fma_f32 v255, -v33, v123, v255
	v_fma_f32 v0, -v30, v124, v0
	v_add_f32_e32 v254, v0, v254
	v_add_f32_e32 v31, v254, v255
	ds_read_b128 v[122:125], v1 offset:27648
	ds_read_b128 v[126:129], v1 offset:27664
	ds_read_b128 v[130:133], v1 offset:27680
	ds_read_b128 v[220:223], v1 offset:27696
	s_waitcnt lgkmcnt(3)
	v_fma_f32 v0, -v2, v122, v28
	v_mul_f32_e64 v254, -v3, v123
	v_mul_f32_e64 v255, -v9, v124
	v_fma_f32 v0, -v50, v125, v0
	s_waitcnt lgkmcnt(2)
	v_fma_f32 v254, -v51, v126, v254
	v_fma_f32 v255, -v54, v127, v255
	v_fma_f32 v0, -v55, v128, v0
	v_fma_f32 v254, -v56, v129, v254
	s_waitcnt lgkmcnt(1)
	v_fma_f32 v255, -v57, v130, v255
	v_fma_f32 v0, -v58, v131, v0
	v_fma_f32 v254, -v59, v132, v254
	v_fma_f32 v255, -v60, v133, v255
	ds_read_b128 v[122:125], v1 offset:27712
	s_waitcnt lgkmcnt(1)
	v_fma_f32 v0, -v61, v220, v0
	v_fma_f32 v254, -v62, v221, v254
	v_fma_f32 v255, -v63, v222, v255
	v_fma_f32 v0, -v70, v223, v0
	s_waitcnt lgkmcnt(0)
	v_fma_f32 v254, -v68, v122, v254
	v_fma_f32 v255, -v69, v123, v255
	v_fma_f32 v0, -v66, v124, v0
	v_fma_f32 v254, -v67, v125, v254
	ds_read_b128 v[122:125], v1 offset:27728
	s_waitcnt lgkmcnt(0)
	v_fma_f32 v255, -v64, v122, v255
	v_fma_f32 v0, -v65, v123, v0
	v_fma_f32 v254, -v52, v124, v254
	v_fma_f32 v255, -v53, v125, v255
	ds_read_b128 v[122:125], v1 offset:27744
	s_waitcnt lgkmcnt(0)
	v_fma_f32 v0, -v48, v122, v0
	v_fma_f32 v254, -v49, v123, v254
	v_fma_f32 v255, -v46, v124, v255
	v_fma_f32 v0, -v47, v125, v0
	ds_read_b128 v[122:125], v1 offset:27760
	s_waitcnt lgkmcnt(0)
	v_fma_f32 v254, -v44, v122, v254
	v_fma_f32 v255, -v45, v123, v255
	v_fma_f32 v0, -v42, v124, v0
	v_fma_f32 v254, -v43, v125, v254
	ds_read_b128 v[122:125], v1 offset:27776
	s_waitcnt lgkmcnt(0)
	v_fma_f32 v255, -v40, v122, v255
	v_fma_f32 v0, -v41, v123, v0
	v_fma_f32 v254, -v38, v124, v254
	v_fma_f32 v255, -v39, v125, v255
	ds_read_b128 v[122:125], v1 offset:27792
	s_waitcnt lgkmcnt(0)
	v_fma_f32 v0, -v36, v122, v0
	v_fma_f32 v254, -v37, v123, v254
	v_fma_f32 v255, -v34, v124, v255
	v_fma_f32 v0, -v35, v125, v0
	ds_read_b128 v[122:125], v1 offset:27808
	s_waitcnt lgkmcnt(0)
	v_fma_f32 v254, -v32, v122, v254
	v_fma_f32 v255, -v33, v123, v255
	v_fma_f32 v0, -v30, v124, v0
	v_fma_f32 v254, -v31, v125, v254
	v_add_f32_e32 v254, v0, v254
	v_add_f32_e32 v28, v254, v255
	ds_read_b128 v[122:125], v1 offset:27904
	ds_read_b128 v[126:129], v1 offset:27920
	ds_read_b128 v[130:133], v1 offset:27936
	ds_read_b128 v[220:223], v1 offset:27952
	s_waitcnt lgkmcnt(3)
	v_fma_f32 v0, -v2, v122, v29
	v_mul_f32_e64 v254, -v3, v123
	v_mul_f32_e64 v255, -v9, v124
	v_fma_f32 v0, -v50, v125, v0
	s_waitcnt lgkmcnt(2)
	v_fma_f32 v254, -v51, v126, v254
	v_fma_f32 v255, -v54, v127, v255
	v_fma_f32 v0, -v55, v128, v0
	v_fma_f32 v254, -v56, v129, v254
	s_waitcnt lgkmcnt(1)
	v_fma_f32 v255, -v57, v130, v255
	v_fma_f32 v0, -v58, v131, v0
	v_fma_f32 v254, -v59, v132, v254
	v_fma_f32 v255, -v60, v133, v255
	ds_read_b128 v[122:125], v1 offset:27968
	ds_read_b32 v29, v1 offset:28080
	s_waitcnt lgkmcnt(2)
	v_fma_f32 v0, -v61, v220, v0
	v_fma_f32 v254, -v62, v221, v254
	v_fma_f32 v255, -v63, v222, v255
	v_fma_f32 v0, -v70, v223, v0
	s_waitcnt lgkmcnt(1)
	v_fma_f32 v254, -v68, v122, v254
	v_fma_f32 v255, -v69, v123, v255
	v_fma_f32 v0, -v66, v124, v0
	v_fma_f32 v254, -v67, v125, v254
	ds_read_b128 v[122:125], v1 offset:27984
	s_waitcnt lgkmcnt(0)
	v_fma_f32 v255, -v64, v122, v255
	v_fma_f32 v0, -v65, v123, v0
	v_fma_f32 v254, -v52, v124, v254
	v_fma_f32 v255, -v53, v125, v255
	ds_read_b128 v[122:125], v1 offset:28000
	s_waitcnt lgkmcnt(0)
	v_fma_f32 v0, -v48, v122, v0
	v_fma_f32 v254, -v49, v123, v254
	v_fma_f32 v255, -v46, v124, v255
	v_fma_f32 v0, -v47, v125, v0
	ds_read_b128 v[122:125], v1 offset:28016
	s_waitcnt lgkmcnt(0)
	v_fma_f32 v254, -v44, v122, v254
	v_fma_f32 v255, -v45, v123, v255
	v_fma_f32 v0, -v42, v124, v0
	v_fma_f32 v254, -v43, v125, v254
	ds_read_b128 v[122:125], v1 offset:28032
	s_waitcnt lgkmcnt(0)
	v_fma_f32 v255, -v40, v122, v255
	v_fma_f32 v0, -v41, v123, v0
	v_fma_f32 v254, -v38, v124, v254
	v_fma_f32 v255, -v39, v125, v255
	ds_read_b128 v[122:125], v1 offset:28048
	s_waitcnt lgkmcnt(0)
	v_fma_f32 v0, -v36, v122, v0
	v_fma_f32 v254, -v37, v123, v254
	v_fma_f32 v255, -v34, v124, v255
	v_fma_f32 v0, -v35, v125, v0
	ds_read_b128 v[122:125], v1 offset:28064
	s_waitcnt lgkmcnt(0)
	v_fma_f32 v254, -v32, v122, v254
	v_fma_f32 v255, -v33, v123, v255
	v_fma_f32 v0, -v30, v124, v0
	v_fma_f32 v254, -v31, v125, v254
	v_fma_f32 v255, -v28, v29, v255
	v_add_f32_e32 v254, v0, v254
	v_add_f32_e32 v29, v254, v255
	ds_read_b128 v[122:125], v1 offset:28160
	ds_read_b128 v[126:129], v1 offset:28176
	ds_read_b128 v[130:133], v1 offset:28192
	ds_read_b128 v[220:223], v1 offset:28208
	s_waitcnt lgkmcnt(3)
	v_fma_f32 v0, -v2, v122, v26
	v_mul_f32_e64 v254, -v3, v123
	v_mul_f32_e64 v255, -v9, v124
	v_fma_f32 v0, -v50, v125, v0
	s_waitcnt lgkmcnt(2)
	v_fma_f32 v254, -v51, v126, v254
	v_fma_f32 v255, -v54, v127, v255
	v_fma_f32 v0, -v55, v128, v0
	v_fma_f32 v254, -v56, v129, v254
	s_waitcnt lgkmcnt(1)
	v_fma_f32 v255, -v57, v130, v255
	v_fma_f32 v0, -v58, v131, v0
	v_fma_f32 v254, -v59, v132, v254
	v_fma_f32 v255, -v60, v133, v255
	ds_read_b128 v[122:125], v1 offset:28224
	s_waitcnt lgkmcnt(1)
	v_fma_f32 v0, -v61, v220, v0
	v_fma_f32 v254, -v62, v221, v254
	v_fma_f32 v255, -v63, v222, v255
	v_fma_f32 v0, -v70, v223, v0
	s_waitcnt lgkmcnt(0)
	v_fma_f32 v254, -v68, v122, v254
	v_fma_f32 v255, -v69, v123, v255
	v_fma_f32 v0, -v66, v124, v0
	v_fma_f32 v254, -v67, v125, v254
	ds_read_b128 v[122:125], v1 offset:28240
	s_waitcnt lgkmcnt(0)
	v_fma_f32 v255, -v64, v122, v255
	v_fma_f32 v0, -v65, v123, v0
	v_fma_f32 v254, -v52, v124, v254
	v_fma_f32 v255, -v53, v125, v255
	ds_read_b128 v[122:125], v1 offset:28256
	s_waitcnt lgkmcnt(0)
	v_fma_f32 v0, -v48, v122, v0
	v_fma_f32 v254, -v49, v123, v254
	v_fma_f32 v255, -v46, v124, v255
	v_fma_f32 v0, -v47, v125, v0
	ds_read_b128 v[122:125], v1 offset:28272
	s_waitcnt lgkmcnt(0)
	v_fma_f32 v254, -v44, v122, v254
	v_fma_f32 v255, -v45, v123, v255
	v_fma_f32 v0, -v42, v124, v0
	v_fma_f32 v254, -v43, v125, v254
	ds_read_b128 v[122:125], v1 offset:28288
	s_waitcnt lgkmcnt(0)
	v_fma_f32 v255, -v40, v122, v255
	v_fma_f32 v0, -v41, v123, v0
	v_fma_f32 v254, -v38, v124, v254
	v_fma_f32 v255, -v39, v125, v255
	ds_read_b128 v[122:125], v1 offset:28304
	s_waitcnt lgkmcnt(0)
	v_fma_f32 v0, -v36, v122, v0
	v_fma_f32 v254, -v37, v123, v254
	v_fma_f32 v255, -v34, v124, v255
	v_fma_f32 v0, -v35, v125, v0
	ds_read_b128 v[122:125], v1 offset:28320
	s_waitcnt lgkmcnt(0)
	v_fma_f32 v254, -v32, v122, v254
	v_fma_f32 v255, -v33, v123, v255
	ds_read_b64 v[122:123], v1 offset:28336
	v_fma_f32 v0, -v30, v124, v0
	v_fma_f32 v254, -v31, v125, v254
	s_waitcnt lgkmcnt(0)
	v_fma_f32 v255, -v28, v122, v255
	v_fma_f32 v0, -v29, v123, v0
	v_add_f32_e32 v254, v0, v254
	v_add_f32_e32 v26, v254, v255
	ds_read_b128 v[122:125], v1 offset:28416
	ds_read_b128 v[126:129], v1 offset:28432
	ds_read_b128 v[130:133], v1 offset:28448
	ds_read_b128 v[220:223], v1 offset:28464
	s_waitcnt lgkmcnt(3)
	v_fma_f32 v0, -v2, v122, v27
	v_mul_f32_e64 v254, -v3, v123
	v_mul_f32_e64 v255, -v9, v124
	v_fma_f32 v0, -v50, v125, v0
	s_waitcnt lgkmcnt(2)
	v_fma_f32 v254, -v51, v126, v254
	v_fma_f32 v255, -v54, v127, v255
	v_fma_f32 v0, -v55, v128, v0
	v_fma_f32 v254, -v56, v129, v254
	s_waitcnt lgkmcnt(1)
	v_fma_f32 v255, -v57, v130, v255
	v_fma_f32 v0, -v58, v131, v0
	v_fma_f32 v254, -v59, v132, v254
	v_fma_f32 v255, -v60, v133, v255
	ds_read_b128 v[122:125], v1 offset:28480
	s_waitcnt lgkmcnt(1)
	v_fma_f32 v0, -v61, v220, v0
	v_fma_f32 v254, -v62, v221, v254
	v_fma_f32 v255, -v63, v222, v255
	v_fma_f32 v0, -v70, v223, v0
	s_waitcnt lgkmcnt(0)
	v_fma_f32 v254, -v68, v122, v254
	v_fma_f32 v255, -v69, v123, v255
	v_fma_f32 v0, -v66, v124, v0
	v_fma_f32 v254, -v67, v125, v254
	ds_read_b128 v[122:125], v1 offset:28496
	s_waitcnt lgkmcnt(0)
	v_fma_f32 v255, -v64, v122, v255
	v_fma_f32 v0, -v65, v123, v0
	v_fma_f32 v254, -v52, v124, v254
	v_fma_f32 v255, -v53, v125, v255
	ds_read_b128 v[122:125], v1 offset:28512
	s_waitcnt lgkmcnt(0)
	v_fma_f32 v0, -v48, v122, v0
	v_fma_f32 v254, -v49, v123, v254
	v_fma_f32 v255, -v46, v124, v255
	v_fma_f32 v0, -v47, v125, v0
	ds_read_b128 v[122:125], v1 offset:28528
	s_waitcnt lgkmcnt(0)
	v_fma_f32 v254, -v44, v122, v254
	v_fma_f32 v255, -v45, v123, v255
	v_fma_f32 v0, -v42, v124, v0
	v_fma_f32 v254, -v43, v125, v254
	ds_read_b128 v[122:125], v1 offset:28544
	s_waitcnt lgkmcnt(0)
	v_fma_f32 v255, -v40, v122, v255
	v_fma_f32 v0, -v41, v123, v0
	v_fma_f32 v254, -v38, v124, v254
	v_fma_f32 v255, -v39, v125, v255
	ds_read_b128 v[122:125], v1 offset:28560
	s_waitcnt lgkmcnt(0)
	v_fma_f32 v0, -v36, v122, v0
	v_fma_f32 v254, -v37, v123, v254
	v_fma_f32 v255, -v34, v124, v255
	v_fma_f32 v0, -v35, v125, v0
	ds_read_b128 v[122:125], v1 offset:28576
	s_waitcnt lgkmcnt(0)
	v_fma_f32 v254, -v32, v122, v254
	v_fma_f32 v255, -v33, v123, v255
	v_fma_f32 v0, -v30, v124, v0
	ds_read_b96 v[122:124], v1 offset:28592
	v_fma_f32 v254, -v31, v125, v254
	s_waitcnt lgkmcnt(0)
	v_fma_f32 v255, -v28, v122, v255
	v_fma_f32 v0, -v29, v123, v0
	v_fma_f32 v254, -v26, v124, v254
	v_add_f32_e32 v254, v0, v254
	v_add_f32_e32 v27, v254, v255
	ds_read_b128 v[122:125], v1 offset:28672
	ds_read_b128 v[126:129], v1 offset:28688
	ds_read_b128 v[130:133], v1 offset:28704
	ds_read_b128 v[220:223], v1 offset:28720
	s_waitcnt lgkmcnt(3)
	v_fma_f32 v0, -v2, v122, v24
	v_mul_f32_e64 v254, -v3, v123
	v_mul_f32_e64 v255, -v9, v124
	v_fma_f32 v0, -v50, v125, v0
	s_waitcnt lgkmcnt(2)
	v_fma_f32 v254, -v51, v126, v254
	v_fma_f32 v255, -v54, v127, v255
	v_fma_f32 v0, -v55, v128, v0
	v_fma_f32 v254, -v56, v129, v254
	s_waitcnt lgkmcnt(1)
	v_fma_f32 v255, -v57, v130, v255
	v_fma_f32 v0, -v58, v131, v0
	v_fma_f32 v254, -v59, v132, v254
	v_fma_f32 v255, -v60, v133, v255
	ds_read_b128 v[122:125], v1 offset:28736
	s_waitcnt lgkmcnt(1)
	v_fma_f32 v0, -v61, v220, v0
	v_fma_f32 v254, -v62, v221, v254
	v_fma_f32 v255, -v63, v222, v255
	v_fma_f32 v0, -v70, v223, v0
	s_waitcnt lgkmcnt(0)
	v_fma_f32 v254, -v68, v122, v254
	v_fma_f32 v255, -v69, v123, v255
	v_fma_f32 v0, -v66, v124, v0
	v_fma_f32 v254, -v67, v125, v254
	ds_read_b128 v[122:125], v1 offset:28752
	s_waitcnt lgkmcnt(0)
	v_fma_f32 v255, -v64, v122, v255
	v_fma_f32 v0, -v65, v123, v0
	v_fma_f32 v254, -v52, v124, v254
	v_fma_f32 v255, -v53, v125, v255
	ds_read_b128 v[122:125], v1 offset:28768
	s_waitcnt lgkmcnt(0)
	v_fma_f32 v0, -v48, v122, v0
	v_fma_f32 v254, -v49, v123, v254
	v_fma_f32 v255, -v46, v124, v255
	v_fma_f32 v0, -v47, v125, v0
	ds_read_b128 v[122:125], v1 offset:28784
	s_waitcnt lgkmcnt(0)
	v_fma_f32 v254, -v44, v122, v254
	v_fma_f32 v255, -v45, v123, v255
	v_fma_f32 v0, -v42, v124, v0
	v_fma_f32 v254, -v43, v125, v254
	ds_read_b128 v[122:125], v1 offset:28800
	s_waitcnt lgkmcnt(0)
	v_fma_f32 v255, -v40, v122, v255
	v_fma_f32 v0, -v41, v123, v0
	v_fma_f32 v254, -v38, v124, v254
	v_fma_f32 v255, -v39, v125, v255
	ds_read_b128 v[122:125], v1 offset:28816
	s_waitcnt lgkmcnt(0)
	v_fma_f32 v0, -v36, v122, v0
	v_fma_f32 v254, -v37, v123, v254
	v_fma_f32 v255, -v34, v124, v255
	v_fma_f32 v0, -v35, v125, v0
	ds_read_b128 v[122:125], v1 offset:28832
	s_waitcnt lgkmcnt(0)
	v_fma_f32 v254, -v32, v122, v254
	v_fma_f32 v255, -v33, v123, v255
	v_fma_f32 v0, -v30, v124, v0
	v_fma_f32 v254, -v31, v125, v254
	ds_read_b128 v[122:125], v1 offset:28848
	s_waitcnt lgkmcnt(0)
	v_fma_f32 v255, -v28, v122, v255
	v_fma_f32 v0, -v29, v123, v0
	v_fma_f32 v254, -v26, v124, v254
	v_fma_f32 v255, -v27, v125, v255
	v_add_f32_e32 v254, v0, v254
	v_add_f32_e32 v24, v254, v255
	ds_read_b128 v[122:125], v1 offset:28928
	ds_read_b128 v[126:129], v1 offset:28944
	ds_read_b128 v[130:133], v1 offset:28960
	ds_read_b128 v[220:223], v1 offset:28976
	s_waitcnt lgkmcnt(3)
	v_fma_f32 v0, -v2, v122, v25
	v_mul_f32_e64 v254, -v3, v123
	v_mul_f32_e64 v255, -v9, v124
	v_fma_f32 v0, -v50, v125, v0
	s_waitcnt lgkmcnt(2)
	v_fma_f32 v254, -v51, v126, v254
	v_fma_f32 v255, -v54, v127, v255
	v_fma_f32 v0, -v55, v128, v0
	v_fma_f32 v254, -v56, v129, v254
	s_waitcnt lgkmcnt(1)
	v_fma_f32 v255, -v57, v130, v255
	v_fma_f32 v0, -v58, v131, v0
	v_fma_f32 v254, -v59, v132, v254
	v_fma_f32 v255, -v60, v133, v255
	ds_read_b128 v[122:125], v1 offset:28992
	ds_read_b32 v25, v1 offset:29120
	s_waitcnt lgkmcnt(2)
	v_fma_f32 v0, -v61, v220, v0
	v_fma_f32 v254, -v62, v221, v254
	v_fma_f32 v255, -v63, v222, v255
	v_fma_f32 v0, -v70, v223, v0
	s_waitcnt lgkmcnt(1)
	v_fma_f32 v254, -v68, v122, v254
	v_fma_f32 v255, -v69, v123, v255
	v_fma_f32 v0, -v66, v124, v0
	v_fma_f32 v254, -v67, v125, v254
	ds_read_b128 v[122:125], v1 offset:29008
	s_waitcnt lgkmcnt(0)
	v_fma_f32 v255, -v64, v122, v255
	v_fma_f32 v0, -v65, v123, v0
	v_fma_f32 v254, -v52, v124, v254
	v_fma_f32 v255, -v53, v125, v255
	ds_read_b128 v[122:125], v1 offset:29024
	s_waitcnt lgkmcnt(0)
	v_fma_f32 v0, -v48, v122, v0
	v_fma_f32 v254, -v49, v123, v254
	v_fma_f32 v255, -v46, v124, v255
	v_fma_f32 v0, -v47, v125, v0
	ds_read_b128 v[122:125], v1 offset:29040
	s_waitcnt lgkmcnt(0)
	v_fma_f32 v254, -v44, v122, v254
	v_fma_f32 v255, -v45, v123, v255
	v_fma_f32 v0, -v42, v124, v0
	v_fma_f32 v254, -v43, v125, v254
	ds_read_b128 v[122:125], v1 offset:29056
	s_waitcnt lgkmcnt(0)
	v_fma_f32 v255, -v40, v122, v255
	v_fma_f32 v0, -v41, v123, v0
	v_fma_f32 v254, -v38, v124, v254
	v_fma_f32 v255, -v39, v125, v255
	ds_read_b128 v[122:125], v1 offset:29072
	s_waitcnt lgkmcnt(0)
	v_fma_f32 v0, -v36, v122, v0
	v_fma_f32 v254, -v37, v123, v254
	v_fma_f32 v255, -v34, v124, v255
	v_fma_f32 v0, -v35, v125, v0
	ds_read_b128 v[122:125], v1 offset:29088
	s_waitcnt lgkmcnt(0)
	v_fma_f32 v254, -v32, v122, v254
	v_fma_f32 v255, -v33, v123, v255
	v_fma_f32 v0, -v30, v124, v0
	v_fma_f32 v254, -v31, v125, v254
	ds_read_b128 v[122:125], v1 offset:29104
	s_waitcnt lgkmcnt(0)
	v_fma_f32 v255, -v28, v122, v255
	v_fma_f32 v0, -v29, v123, v0
	v_fma_f32 v254, -v26, v124, v254
	v_fma_f32 v255, -v27, v125, v255
	v_fma_f32 v0, -v24, v25, v0
	v_add_f32_e32 v254, v0, v254
	v_add_f32_e32 v25, v254, v255
	ds_read_b128 v[122:125], v1 offset:29184
	ds_read_b128 v[126:129], v1 offset:29200
	ds_read_b128 v[130:133], v1 offset:29216
	ds_read_b128 v[220:223], v1 offset:29232
	s_waitcnt lgkmcnt(3)
	v_fma_f32 v0, -v2, v122, v22
	v_mul_f32_e64 v254, -v3, v123
	v_mul_f32_e64 v255, -v9, v124
	v_fma_f32 v0, -v50, v125, v0
	s_waitcnt lgkmcnt(2)
	v_fma_f32 v254, -v51, v126, v254
	v_fma_f32 v255, -v54, v127, v255
	v_fma_f32 v0, -v55, v128, v0
	v_fma_f32 v254, -v56, v129, v254
	s_waitcnt lgkmcnt(1)
	v_fma_f32 v255, -v57, v130, v255
	v_fma_f32 v0, -v58, v131, v0
	v_fma_f32 v254, -v59, v132, v254
	v_fma_f32 v255, -v60, v133, v255
	ds_read_b128 v[122:125], v1 offset:29248
	s_waitcnt lgkmcnt(1)
	v_fma_f32 v0, -v61, v220, v0
	v_fma_f32 v254, -v62, v221, v254
	v_fma_f32 v255, -v63, v222, v255
	v_fma_f32 v0, -v70, v223, v0
	s_waitcnt lgkmcnt(0)
	v_fma_f32 v254, -v68, v122, v254
	v_fma_f32 v255, -v69, v123, v255
	v_fma_f32 v0, -v66, v124, v0
	v_fma_f32 v254, -v67, v125, v254
	ds_read_b128 v[122:125], v1 offset:29264
	s_waitcnt lgkmcnt(0)
	v_fma_f32 v255, -v64, v122, v255
	v_fma_f32 v0, -v65, v123, v0
	v_fma_f32 v254, -v52, v124, v254
	v_fma_f32 v255, -v53, v125, v255
	ds_read_b128 v[122:125], v1 offset:29280
	s_waitcnt lgkmcnt(0)
	v_fma_f32 v0, -v48, v122, v0
	v_fma_f32 v254, -v49, v123, v254
	v_fma_f32 v255, -v46, v124, v255
	v_fma_f32 v0, -v47, v125, v0
	ds_read_b128 v[122:125], v1 offset:29296
	s_waitcnt lgkmcnt(0)
	v_fma_f32 v254, -v44, v122, v254
	v_fma_f32 v255, -v45, v123, v255
	v_fma_f32 v0, -v42, v124, v0
	v_fma_f32 v254, -v43, v125, v254
	ds_read_b128 v[122:125], v1 offset:29312
	s_waitcnt lgkmcnt(0)
	v_fma_f32 v255, -v40, v122, v255
	v_fma_f32 v0, -v41, v123, v0
	v_fma_f32 v254, -v38, v124, v254
	v_fma_f32 v255, -v39, v125, v255
	ds_read_b128 v[122:125], v1 offset:29328
	s_waitcnt lgkmcnt(0)
	v_fma_f32 v0, -v36, v122, v0
	v_fma_f32 v254, -v37, v123, v254
	v_fma_f32 v255, -v34, v124, v255
	v_fma_f32 v0, -v35, v125, v0
	ds_read_b128 v[122:125], v1 offset:29344
	s_waitcnt lgkmcnt(0)
	v_fma_f32 v254, -v32, v122, v254
	v_fma_f32 v255, -v33, v123, v255
	v_fma_f32 v0, -v30, v124, v0
	v_fma_f32 v254, -v31, v125, v254
	ds_read_b128 v[122:125], v1 offset:29360
	s_waitcnt lgkmcnt(0)
	v_fma_f32 v255, -v28, v122, v255
	v_fma_f32 v0, -v29, v123, v0
	ds_read_b64 v[122:123], v1 offset:29376
	v_fma_f32 v254, -v26, v124, v254
	v_fma_f32 v255, -v27, v125, v255
	s_waitcnt lgkmcnt(0)
	v_fma_f32 v0, -v24, v122, v0
	v_fma_f32 v254, -v25, v123, v254
	v_add_f32_e32 v254, v0, v254
	v_add_f32_e32 v22, v254, v255
	ds_read_b128 v[122:125], v1 offset:29440
	ds_read_b128 v[126:129], v1 offset:29456
	ds_read_b128 v[130:133], v1 offset:29472
	ds_read_b128 v[220:223], v1 offset:29488
	s_waitcnt lgkmcnt(3)
	v_fma_f32 v0, -v2, v122, v23
	v_mul_f32_e64 v254, -v3, v123
	v_mul_f32_e64 v255, -v9, v124
	v_fma_f32 v0, -v50, v125, v0
	s_waitcnt lgkmcnt(2)
	v_fma_f32 v254, -v51, v126, v254
	v_fma_f32 v255, -v54, v127, v255
	v_fma_f32 v0, -v55, v128, v0
	v_fma_f32 v254, -v56, v129, v254
	s_waitcnt lgkmcnt(1)
	v_fma_f32 v255, -v57, v130, v255
	v_fma_f32 v0, -v58, v131, v0
	v_fma_f32 v254, -v59, v132, v254
	v_fma_f32 v255, -v60, v133, v255
	ds_read_b128 v[122:125], v1 offset:29504
	s_waitcnt lgkmcnt(1)
	v_fma_f32 v0, -v61, v220, v0
	v_fma_f32 v254, -v62, v221, v254
	v_fma_f32 v255, -v63, v222, v255
	v_fma_f32 v0, -v70, v223, v0
	s_waitcnt lgkmcnt(0)
	v_fma_f32 v254, -v68, v122, v254
	v_fma_f32 v255, -v69, v123, v255
	v_fma_f32 v0, -v66, v124, v0
	v_fma_f32 v254, -v67, v125, v254
	ds_read_b128 v[122:125], v1 offset:29520
	s_waitcnt lgkmcnt(0)
	v_fma_f32 v255, -v64, v122, v255
	v_fma_f32 v0, -v65, v123, v0
	v_fma_f32 v254, -v52, v124, v254
	v_fma_f32 v255, -v53, v125, v255
	ds_read_b128 v[122:125], v1 offset:29536
	s_waitcnt lgkmcnt(0)
	v_fma_f32 v0, -v48, v122, v0
	v_fma_f32 v254, -v49, v123, v254
	v_fma_f32 v255, -v46, v124, v255
	v_fma_f32 v0, -v47, v125, v0
	ds_read_b128 v[122:125], v1 offset:29552
	s_waitcnt lgkmcnt(0)
	v_fma_f32 v254, -v44, v122, v254
	v_fma_f32 v255, -v45, v123, v255
	v_fma_f32 v0, -v42, v124, v0
	v_fma_f32 v254, -v43, v125, v254
	ds_read_b128 v[122:125], v1 offset:29568
	s_waitcnt lgkmcnt(0)
	v_fma_f32 v255, -v40, v122, v255
	v_fma_f32 v0, -v41, v123, v0
	v_fma_f32 v254, -v38, v124, v254
	v_fma_f32 v255, -v39, v125, v255
	ds_read_b128 v[122:125], v1 offset:29584
	s_waitcnt lgkmcnt(0)
	v_fma_f32 v0, -v36, v122, v0
	v_fma_f32 v254, -v37, v123, v254
	v_fma_f32 v255, -v34, v124, v255
	v_fma_f32 v0, -v35, v125, v0
	ds_read_b128 v[122:125], v1 offset:29600
	s_waitcnt lgkmcnt(0)
	v_fma_f32 v254, -v32, v122, v254
	v_fma_f32 v255, -v33, v123, v255
	v_fma_f32 v0, -v30, v124, v0
	v_fma_f32 v254, -v31, v125, v254
	ds_read_b128 v[122:125], v1 offset:29616
	s_waitcnt lgkmcnt(0)
	v_fma_f32 v255, -v28, v122, v255
	v_fma_f32 v0, -v29, v123, v0
	v_fma_f32 v254, -v26, v124, v254
	ds_read_b96 v[122:124], v1 offset:29632
	v_fma_f32 v255, -v27, v125, v255
	s_waitcnt lgkmcnt(0)
	v_fma_f32 v0, -v24, v122, v0
	v_fma_f32 v254, -v25, v123, v254
	v_fma_f32 v255, -v22, v124, v255
	v_add_f32_e32 v254, v0, v254
	v_add_f32_e32 v23, v254, v255
	ds_read_b128 v[122:125], v1 offset:29696
	ds_read_b128 v[126:129], v1 offset:29712
	ds_read_b128 v[130:133], v1 offset:29728
	ds_read_b128 v[220:223], v1 offset:29744
	s_waitcnt lgkmcnt(3)
	v_fma_f32 v0, -v2, v122, v20
	v_mul_f32_e64 v254, -v3, v123
	v_mul_f32_e64 v255, -v9, v124
	v_fma_f32 v0, -v50, v125, v0
	s_waitcnt lgkmcnt(2)
	v_fma_f32 v254, -v51, v126, v254
	v_fma_f32 v255, -v54, v127, v255
	v_fma_f32 v0, -v55, v128, v0
	v_fma_f32 v254, -v56, v129, v254
	s_waitcnt lgkmcnt(1)
	v_fma_f32 v255, -v57, v130, v255
	v_fma_f32 v0, -v58, v131, v0
	v_fma_f32 v254, -v59, v132, v254
	v_fma_f32 v255, -v60, v133, v255
	ds_read_b128 v[122:125], v1 offset:29760
	s_waitcnt lgkmcnt(1)
	v_fma_f32 v0, -v61, v220, v0
	v_fma_f32 v254, -v62, v221, v254
	v_fma_f32 v255, -v63, v222, v255
	v_fma_f32 v0, -v70, v223, v0
	s_waitcnt lgkmcnt(0)
	v_fma_f32 v254, -v68, v122, v254
	v_fma_f32 v255, -v69, v123, v255
	v_fma_f32 v0, -v66, v124, v0
	v_fma_f32 v254, -v67, v125, v254
	ds_read_b128 v[122:125], v1 offset:29776
	s_waitcnt lgkmcnt(0)
	v_fma_f32 v255, -v64, v122, v255
	v_fma_f32 v0, -v65, v123, v0
	v_fma_f32 v254, -v52, v124, v254
	v_fma_f32 v255, -v53, v125, v255
	ds_read_b128 v[122:125], v1 offset:29792
	s_waitcnt lgkmcnt(0)
	v_fma_f32 v0, -v48, v122, v0
	v_fma_f32 v254, -v49, v123, v254
	v_fma_f32 v255, -v46, v124, v255
	v_fma_f32 v0, -v47, v125, v0
	ds_read_b128 v[122:125], v1 offset:29808
	s_waitcnt lgkmcnt(0)
	v_fma_f32 v254, -v44, v122, v254
	v_fma_f32 v255, -v45, v123, v255
	v_fma_f32 v0, -v42, v124, v0
	v_fma_f32 v254, -v43, v125, v254
	ds_read_b128 v[122:125], v1 offset:29824
	s_waitcnt lgkmcnt(0)
	v_fma_f32 v255, -v40, v122, v255
	v_fma_f32 v0, -v41, v123, v0
	v_fma_f32 v254, -v38, v124, v254
	v_fma_f32 v255, -v39, v125, v255
	ds_read_b128 v[122:125], v1 offset:29840
	s_waitcnt lgkmcnt(0)
	v_fma_f32 v0, -v36, v122, v0
	v_fma_f32 v254, -v37, v123, v254
	v_fma_f32 v255, -v34, v124, v255
	v_fma_f32 v0, -v35, v125, v0
	ds_read_b128 v[122:125], v1 offset:29856
	s_waitcnt lgkmcnt(0)
	v_fma_f32 v254, -v32, v122, v254
	v_fma_f32 v255, -v33, v123, v255
	v_fma_f32 v0, -v30, v124, v0
	v_fma_f32 v254, -v31, v125, v254
	ds_read_b128 v[122:125], v1 offset:29872
	s_waitcnt lgkmcnt(0)
	v_fma_f32 v255, -v28, v122, v255
	v_fma_f32 v0, -v29, v123, v0
	v_fma_f32 v254, -v26, v124, v254
	v_fma_f32 v255, -v27, v125, v255
	ds_read_b128 v[122:125], v1 offset:29888
	s_waitcnt lgkmcnt(0)
	v_fma_f32 v0, -v24, v122, v0
	v_fma_f32 v254, -v25, v123, v254
	v_fma_f32 v255, -v22, v124, v255
	v_fma_f32 v0, -v23, v125, v0
	v_add_f32_e32 v254, v0, v254
	v_add_f32_e32 v20, v254, v255
	ds_read_b128 v[122:125], v1 offset:29952
	ds_read_b128 v[126:129], v1 offset:29968
	ds_read_b128 v[130:133], v1 offset:29984
	ds_read_b128 v[220:223], v1 offset:30000
	s_waitcnt lgkmcnt(3)
	v_fma_f32 v0, -v2, v122, v21
	v_mul_f32_e64 v254, -v3, v123
	v_mul_f32_e64 v255, -v9, v124
	v_fma_f32 v0, -v50, v125, v0
	s_waitcnt lgkmcnt(2)
	v_fma_f32 v254, -v51, v126, v254
	v_fma_f32 v255, -v54, v127, v255
	v_fma_f32 v0, -v55, v128, v0
	v_fma_f32 v254, -v56, v129, v254
	s_waitcnt lgkmcnt(1)
	v_fma_f32 v255, -v57, v130, v255
	v_fma_f32 v0, -v58, v131, v0
	v_fma_f32 v254, -v59, v132, v254
	v_fma_f32 v255, -v60, v133, v255
	ds_read_b128 v[122:125], v1 offset:30016
	ds_read_b32 v21, v1 offset:30160
	s_waitcnt lgkmcnt(2)
	v_fma_f32 v0, -v61, v220, v0
	v_fma_f32 v254, -v62, v221, v254
	v_fma_f32 v255, -v63, v222, v255
	v_fma_f32 v0, -v70, v223, v0
	s_waitcnt lgkmcnt(1)
	v_fma_f32 v254, -v68, v122, v254
	v_fma_f32 v255, -v69, v123, v255
	v_fma_f32 v0, -v66, v124, v0
	v_fma_f32 v254, -v67, v125, v254
	ds_read_b128 v[122:125], v1 offset:30032
	s_waitcnt lgkmcnt(0)
	v_fma_f32 v255, -v64, v122, v255
	v_fma_f32 v0, -v65, v123, v0
	v_fma_f32 v254, -v52, v124, v254
	v_fma_f32 v255, -v53, v125, v255
	ds_read_b128 v[122:125], v1 offset:30048
	s_waitcnt lgkmcnt(0)
	v_fma_f32 v0, -v48, v122, v0
	v_fma_f32 v254, -v49, v123, v254
	v_fma_f32 v255, -v46, v124, v255
	v_fma_f32 v0, -v47, v125, v0
	ds_read_b128 v[122:125], v1 offset:30064
	s_waitcnt lgkmcnt(0)
	v_fma_f32 v254, -v44, v122, v254
	v_fma_f32 v255, -v45, v123, v255
	v_fma_f32 v0, -v42, v124, v0
	v_fma_f32 v254, -v43, v125, v254
	ds_read_b128 v[122:125], v1 offset:30080
	s_waitcnt lgkmcnt(0)
	v_fma_f32 v255, -v40, v122, v255
	v_fma_f32 v0, -v41, v123, v0
	v_fma_f32 v254, -v38, v124, v254
	v_fma_f32 v255, -v39, v125, v255
	ds_read_b128 v[122:125], v1 offset:30096
	s_waitcnt lgkmcnt(0)
	v_fma_f32 v0, -v36, v122, v0
	v_fma_f32 v254, -v37, v123, v254
	v_fma_f32 v255, -v34, v124, v255
	v_fma_f32 v0, -v35, v125, v0
	ds_read_b128 v[122:125], v1 offset:30112
	s_waitcnt lgkmcnt(0)
	v_fma_f32 v254, -v32, v122, v254
	v_fma_f32 v255, -v33, v123, v255
	v_fma_f32 v0, -v30, v124, v0
	v_fma_f32 v254, -v31, v125, v254
	ds_read_b128 v[122:125], v1 offset:30128
	s_waitcnt lgkmcnt(0)
	v_fma_f32 v255, -v28, v122, v255
	v_fma_f32 v0, -v29, v123, v0
	v_fma_f32 v254, -v26, v124, v254
	v_fma_f32 v255, -v27, v125, v255
	ds_read_b128 v[122:125], v1 offset:30144
	s_waitcnt lgkmcnt(0)
	v_fma_f32 v0, -v24, v122, v0
	v_fma_f32 v254, -v25, v123, v254
	v_fma_f32 v255, -v22, v124, v255
	v_fma_f32 v0, -v23, v125, v0
	v_fma_f32 v254, -v20, v21, v254
	v_add_f32_e32 v254, v0, v254
	v_add_f32_e32 v21, v254, v255
	ds_read_b128 v[122:125], v1 offset:30208
	ds_read_b128 v[126:129], v1 offset:30224
	ds_read_b128 v[130:133], v1 offset:30240
	ds_read_b128 v[220:223], v1 offset:30256
	s_waitcnt lgkmcnt(3)
	v_fma_f32 v0, -v2, v122, v18
	v_mul_f32_e64 v254, -v3, v123
	v_mul_f32_e64 v255, -v9, v124
	v_fma_f32 v0, -v50, v125, v0
	s_waitcnt lgkmcnt(2)
	v_fma_f32 v254, -v51, v126, v254
	v_fma_f32 v255, -v54, v127, v255
	v_fma_f32 v0, -v55, v128, v0
	v_fma_f32 v254, -v56, v129, v254
	s_waitcnt lgkmcnt(1)
	v_fma_f32 v255, -v57, v130, v255
	v_fma_f32 v0, -v58, v131, v0
	v_fma_f32 v254, -v59, v132, v254
	v_fma_f32 v255, -v60, v133, v255
	ds_read_b128 v[122:125], v1 offset:30272
	s_waitcnt lgkmcnt(1)
	v_fma_f32 v0, -v61, v220, v0
	v_fma_f32 v254, -v62, v221, v254
	v_fma_f32 v255, -v63, v222, v255
	v_fma_f32 v0, -v70, v223, v0
	s_waitcnt lgkmcnt(0)
	v_fma_f32 v254, -v68, v122, v254
	v_fma_f32 v255, -v69, v123, v255
	v_fma_f32 v0, -v66, v124, v0
	v_fma_f32 v254, -v67, v125, v254
	ds_read_b128 v[122:125], v1 offset:30288
	s_waitcnt lgkmcnt(0)
	v_fma_f32 v255, -v64, v122, v255
	v_fma_f32 v0, -v65, v123, v0
	v_fma_f32 v254, -v52, v124, v254
	v_fma_f32 v255, -v53, v125, v255
	ds_read_b128 v[122:125], v1 offset:30304
	s_waitcnt lgkmcnt(0)
	v_fma_f32 v0, -v48, v122, v0
	v_fma_f32 v254, -v49, v123, v254
	v_fma_f32 v255, -v46, v124, v255
	v_fma_f32 v0, -v47, v125, v0
	ds_read_b128 v[122:125], v1 offset:30320
	s_waitcnt lgkmcnt(0)
	v_fma_f32 v254, -v44, v122, v254
	v_fma_f32 v255, -v45, v123, v255
	v_fma_f32 v0, -v42, v124, v0
	v_fma_f32 v254, -v43, v125, v254
	ds_read_b128 v[122:125], v1 offset:30336
	s_waitcnt lgkmcnt(0)
	v_fma_f32 v255, -v40, v122, v255
	v_fma_f32 v0, -v41, v123, v0
	v_fma_f32 v254, -v38, v124, v254
	v_fma_f32 v255, -v39, v125, v255
	ds_read_b128 v[122:125], v1 offset:30352
	s_waitcnt lgkmcnt(0)
	v_fma_f32 v0, -v36, v122, v0
	v_fma_f32 v254, -v37, v123, v254
	v_fma_f32 v255, -v34, v124, v255
	v_fma_f32 v0, -v35, v125, v0
	ds_read_b128 v[122:125], v1 offset:30368
	s_waitcnt lgkmcnt(0)
	v_fma_f32 v254, -v32, v122, v254
	v_fma_f32 v255, -v33, v123, v255
	v_fma_f32 v0, -v30, v124, v0
	v_fma_f32 v254, -v31, v125, v254
	ds_read_b128 v[122:125], v1 offset:30384
	s_waitcnt lgkmcnt(0)
	v_fma_f32 v255, -v28, v122, v255
	v_fma_f32 v0, -v29, v123, v0
	v_fma_f32 v254, -v26, v124, v254
	v_fma_f32 v255, -v27, v125, v255
	ds_read_b128 v[122:125], v1 offset:30400
	s_waitcnt lgkmcnt(0)
	v_fma_f32 v0, -v24, v122, v0
	v_fma_f32 v254, -v25, v123, v254
	ds_read_b64 v[122:123], v1 offset:30416
	v_fma_f32 v255, -v22, v124, v255
	v_fma_f32 v0, -v23, v125, v0
	s_waitcnt lgkmcnt(0)
	v_fma_f32 v254, -v20, v122, v254
	v_fma_f32 v255, -v21, v123, v255
	v_add_f32_e32 v254, v0, v254
	v_add_f32_e32 v18, v254, v255
	ds_read_b128 v[122:125], v1 offset:30464
	ds_read_b128 v[126:129], v1 offset:30480
	ds_read_b128 v[130:133], v1 offset:30496
	ds_read_b128 v[220:223], v1 offset:30512
	s_waitcnt lgkmcnt(3)
	v_fma_f32 v0, -v2, v122, v19
	v_mul_f32_e64 v254, -v3, v123
	v_mul_f32_e64 v255, -v9, v124
	v_fma_f32 v0, -v50, v125, v0
	s_waitcnt lgkmcnt(2)
	v_fma_f32 v254, -v51, v126, v254
	v_fma_f32 v255, -v54, v127, v255
	v_fma_f32 v0, -v55, v128, v0
	v_fma_f32 v254, -v56, v129, v254
	s_waitcnt lgkmcnt(1)
	v_fma_f32 v255, -v57, v130, v255
	v_fma_f32 v0, -v58, v131, v0
	v_fma_f32 v254, -v59, v132, v254
	v_fma_f32 v255, -v60, v133, v255
	ds_read_b128 v[122:125], v1 offset:30528
	s_waitcnt lgkmcnt(1)
	v_fma_f32 v0, -v61, v220, v0
	v_fma_f32 v254, -v62, v221, v254
	v_fma_f32 v255, -v63, v222, v255
	v_fma_f32 v0, -v70, v223, v0
	s_waitcnt lgkmcnt(0)
	v_fma_f32 v254, -v68, v122, v254
	v_fma_f32 v255, -v69, v123, v255
	v_fma_f32 v0, -v66, v124, v0
	v_fma_f32 v254, -v67, v125, v254
	ds_read_b128 v[122:125], v1 offset:30544
	s_waitcnt lgkmcnt(0)
	v_fma_f32 v255, -v64, v122, v255
	v_fma_f32 v0, -v65, v123, v0
	v_fma_f32 v254, -v52, v124, v254
	v_fma_f32 v255, -v53, v125, v255
	ds_read_b128 v[122:125], v1 offset:30560
	s_waitcnt lgkmcnt(0)
	v_fma_f32 v0, -v48, v122, v0
	v_fma_f32 v254, -v49, v123, v254
	v_fma_f32 v255, -v46, v124, v255
	v_fma_f32 v0, -v47, v125, v0
	ds_read_b128 v[122:125], v1 offset:30576
	s_waitcnt lgkmcnt(0)
	v_fma_f32 v254, -v44, v122, v254
	v_fma_f32 v255, -v45, v123, v255
	v_fma_f32 v0, -v42, v124, v0
	v_fma_f32 v254, -v43, v125, v254
	ds_read_b128 v[122:125], v1 offset:30592
	s_waitcnt lgkmcnt(0)
	v_fma_f32 v255, -v40, v122, v255
	v_fma_f32 v0, -v41, v123, v0
	v_fma_f32 v254, -v38, v124, v254
	v_fma_f32 v255, -v39, v125, v255
	ds_read_b128 v[122:125], v1 offset:30608
	s_waitcnt lgkmcnt(0)
	v_fma_f32 v0, -v36, v122, v0
	v_fma_f32 v254, -v37, v123, v254
	v_fma_f32 v255, -v34, v124, v255
	v_fma_f32 v0, -v35, v125, v0
	ds_read_b128 v[122:125], v1 offset:30624
	s_waitcnt lgkmcnt(0)
	v_fma_f32 v254, -v32, v122, v254
	v_fma_f32 v255, -v33, v123, v255
	v_fma_f32 v0, -v30, v124, v0
	v_fma_f32 v254, -v31, v125, v254
	ds_read_b128 v[122:125], v1 offset:30640
	s_waitcnt lgkmcnt(0)
	v_fma_f32 v255, -v28, v122, v255
	v_fma_f32 v0, -v29, v123, v0
	v_fma_f32 v254, -v26, v124, v254
	v_fma_f32 v255, -v27, v125, v255
	ds_read_b128 v[122:125], v1 offset:30656
	s_waitcnt lgkmcnt(0)
	v_fma_f32 v0, -v24, v122, v0
	v_fma_f32 v254, -v25, v123, v254
	v_fma_f32 v255, -v22, v124, v255
	ds_read_b96 v[122:124], v1 offset:30672
	v_fma_f32 v0, -v23, v125, v0
	s_waitcnt lgkmcnt(0)
	v_fma_f32 v254, -v20, v122, v254
	v_fma_f32 v255, -v21, v123, v255
	v_fma_f32 v0, -v18, v124, v0
	v_add_f32_e32 v254, v0, v254
	v_add_f32_e32 v19, v254, v255
	ds_read_b128 v[122:125], v1 offset:30720
	ds_read_b128 v[126:129], v1 offset:30736
	ds_read_b128 v[130:133], v1 offset:30752
	ds_read_b128 v[220:223], v1 offset:30768
	s_waitcnt lgkmcnt(3)
	v_fma_f32 v0, -v2, v122, v16
	v_mul_f32_e64 v254, -v3, v123
	v_mul_f32_e64 v255, -v9, v124
	v_fma_f32 v0, -v50, v125, v0
	s_waitcnt lgkmcnt(2)
	v_fma_f32 v254, -v51, v126, v254
	v_fma_f32 v255, -v54, v127, v255
	v_fma_f32 v0, -v55, v128, v0
	v_fma_f32 v254, -v56, v129, v254
	s_waitcnt lgkmcnt(1)
	v_fma_f32 v255, -v57, v130, v255
	v_fma_f32 v0, -v58, v131, v0
	v_fma_f32 v254, -v59, v132, v254
	v_fma_f32 v255, -v60, v133, v255
	ds_read_b128 v[122:125], v1 offset:30784
	s_waitcnt lgkmcnt(1)
	v_fma_f32 v0, -v61, v220, v0
	v_fma_f32 v254, -v62, v221, v254
	v_fma_f32 v255, -v63, v222, v255
	v_fma_f32 v0, -v70, v223, v0
	s_waitcnt lgkmcnt(0)
	v_fma_f32 v254, -v68, v122, v254
	v_fma_f32 v255, -v69, v123, v255
	v_fma_f32 v0, -v66, v124, v0
	v_fma_f32 v254, -v67, v125, v254
	ds_read_b128 v[122:125], v1 offset:30800
	s_waitcnt lgkmcnt(0)
	v_fma_f32 v255, -v64, v122, v255
	v_fma_f32 v0, -v65, v123, v0
	v_fma_f32 v254, -v52, v124, v254
	v_fma_f32 v255, -v53, v125, v255
	ds_read_b128 v[122:125], v1 offset:30816
	s_waitcnt lgkmcnt(0)
	v_fma_f32 v0, -v48, v122, v0
	v_fma_f32 v254, -v49, v123, v254
	v_fma_f32 v255, -v46, v124, v255
	v_fma_f32 v0, -v47, v125, v0
	ds_read_b128 v[122:125], v1 offset:30832
	s_waitcnt lgkmcnt(0)
	v_fma_f32 v254, -v44, v122, v254
	v_fma_f32 v255, -v45, v123, v255
	v_fma_f32 v0, -v42, v124, v0
	v_fma_f32 v254, -v43, v125, v254
	ds_read_b128 v[122:125], v1 offset:30848
	s_waitcnt lgkmcnt(0)
	v_fma_f32 v255, -v40, v122, v255
	v_fma_f32 v0, -v41, v123, v0
	v_fma_f32 v254, -v38, v124, v254
	v_fma_f32 v255, -v39, v125, v255
	ds_read_b128 v[122:125], v1 offset:30864
	s_waitcnt lgkmcnt(0)
	v_fma_f32 v0, -v36, v122, v0
	v_fma_f32 v254, -v37, v123, v254
	v_fma_f32 v255, -v34, v124, v255
	v_fma_f32 v0, -v35, v125, v0
	ds_read_b128 v[122:125], v1 offset:30880
	s_waitcnt lgkmcnt(0)
	v_fma_f32 v254, -v32, v122, v254
	v_fma_f32 v255, -v33, v123, v255
	v_fma_f32 v0, -v30, v124, v0
	v_fma_f32 v254, -v31, v125, v254
	ds_read_b128 v[122:125], v1 offset:30896
	s_waitcnt lgkmcnt(0)
	v_fma_f32 v255, -v28, v122, v255
	v_fma_f32 v0, -v29, v123, v0
	v_fma_f32 v254, -v26, v124, v254
	v_fma_f32 v255, -v27, v125, v255
	ds_read_b128 v[122:125], v1 offset:30912
	s_waitcnt lgkmcnt(0)
	v_fma_f32 v0, -v24, v122, v0
	v_fma_f32 v254, -v25, v123, v254
	v_fma_f32 v255, -v22, v124, v255
	v_fma_f32 v0, -v23, v125, v0
	ds_read_b128 v[122:125], v1 offset:30928
	s_waitcnt lgkmcnt(0)
	v_fma_f32 v254, -v20, v122, v254
	v_fma_f32 v255, -v21, v123, v255
	v_fma_f32 v0, -v18, v124, v0
	v_fma_f32 v254, -v19, v125, v254
	v_add_f32_e32 v254, v0, v254
	v_add_f32_e32 v16, v254, v255
	ds_read_b128 v[122:125], v1 offset:30976
	ds_read_b128 v[126:129], v1 offset:30992
	ds_read_b128 v[130:133], v1 offset:31008
	ds_read_b128 v[220:223], v1 offset:31024
	s_waitcnt lgkmcnt(3)
	v_fma_f32 v0, -v2, v122, v17
	v_mul_f32_e64 v254, -v3, v123
	v_mul_f32_e64 v255, -v9, v124
	v_fma_f32 v0, -v50, v125, v0
	s_waitcnt lgkmcnt(2)
	v_fma_f32 v254, -v51, v126, v254
	v_fma_f32 v255, -v54, v127, v255
	v_fma_f32 v0, -v55, v128, v0
	v_fma_f32 v254, -v56, v129, v254
	s_waitcnt lgkmcnt(1)
	v_fma_f32 v255, -v57, v130, v255
	v_fma_f32 v0, -v58, v131, v0
	v_fma_f32 v254, -v59, v132, v254
	v_fma_f32 v255, -v60, v133, v255
	ds_read_b128 v[122:125], v1 offset:31040
	ds_read_b32 v17, v1 offset:31200
	s_waitcnt lgkmcnt(2)
	v_fma_f32 v0, -v61, v220, v0
	v_fma_f32 v254, -v62, v221, v254
	v_fma_f32 v255, -v63, v222, v255
	v_fma_f32 v0, -v70, v223, v0
	s_waitcnt lgkmcnt(1)
	v_fma_f32 v254, -v68, v122, v254
	v_fma_f32 v255, -v69, v123, v255
	v_fma_f32 v0, -v66, v124, v0
	v_fma_f32 v254, -v67, v125, v254
	ds_read_b128 v[122:125], v1 offset:31056
	s_waitcnt lgkmcnt(0)
	v_fma_f32 v255, -v64, v122, v255
	v_fma_f32 v0, -v65, v123, v0
	v_fma_f32 v254, -v52, v124, v254
	v_fma_f32 v255, -v53, v125, v255
	ds_read_b128 v[122:125], v1 offset:31072
	s_waitcnt lgkmcnt(0)
	v_fma_f32 v0, -v48, v122, v0
	v_fma_f32 v254, -v49, v123, v254
	v_fma_f32 v255, -v46, v124, v255
	v_fma_f32 v0, -v47, v125, v0
	ds_read_b128 v[122:125], v1 offset:31088
	s_waitcnt lgkmcnt(0)
	v_fma_f32 v254, -v44, v122, v254
	v_fma_f32 v255, -v45, v123, v255
	v_fma_f32 v0, -v42, v124, v0
	v_fma_f32 v254, -v43, v125, v254
	ds_read_b128 v[122:125], v1 offset:31104
	s_waitcnt lgkmcnt(0)
	v_fma_f32 v255, -v40, v122, v255
	v_fma_f32 v0, -v41, v123, v0
	v_fma_f32 v254, -v38, v124, v254
	v_fma_f32 v255, -v39, v125, v255
	ds_read_b128 v[122:125], v1 offset:31120
	s_waitcnt lgkmcnt(0)
	v_fma_f32 v0, -v36, v122, v0
	v_fma_f32 v254, -v37, v123, v254
	v_fma_f32 v255, -v34, v124, v255
	v_fma_f32 v0, -v35, v125, v0
	ds_read_b128 v[122:125], v1 offset:31136
	s_waitcnt lgkmcnt(0)
	v_fma_f32 v254, -v32, v122, v254
	v_fma_f32 v255, -v33, v123, v255
	v_fma_f32 v0, -v30, v124, v0
	v_fma_f32 v254, -v31, v125, v254
	ds_read_b128 v[122:125], v1 offset:31152
	s_waitcnt lgkmcnt(0)
	v_fma_f32 v255, -v28, v122, v255
	v_fma_f32 v0, -v29, v123, v0
	v_fma_f32 v254, -v26, v124, v254
	v_fma_f32 v255, -v27, v125, v255
	ds_read_b128 v[122:125], v1 offset:31168
	s_waitcnt lgkmcnt(0)
	v_fma_f32 v0, -v24, v122, v0
	v_fma_f32 v254, -v25, v123, v254
	v_fma_f32 v255, -v22, v124, v255
	v_fma_f32 v0, -v23, v125, v0
	ds_read_b128 v[122:125], v1 offset:31184
	s_waitcnt lgkmcnt(0)
	v_fma_f32 v254, -v20, v122, v254
	v_fma_f32 v255, -v21, v123, v255
	v_fma_f32 v0, -v18, v124, v0
	v_fma_f32 v254, -v19, v125, v254
	v_fma_f32 v255, -v16, v17, v255
	v_add_f32_e32 v254, v0, v254
	v_add_f32_e32 v17, v254, v255
	ds_read_b128 v[122:125], v1 offset:31232
	ds_read_b128 v[126:129], v1 offset:31248
	ds_read_b128 v[130:133], v1 offset:31264
	ds_read_b128 v[220:223], v1 offset:31280
	s_waitcnt lgkmcnt(3)
	v_fma_f32 v0, -v2, v122, v14
	v_mul_f32_e64 v254, -v3, v123
	v_mul_f32_e64 v255, -v9, v124
	v_fma_f32 v0, -v50, v125, v0
	s_waitcnt lgkmcnt(2)
	v_fma_f32 v254, -v51, v126, v254
	v_fma_f32 v255, -v54, v127, v255
	v_fma_f32 v0, -v55, v128, v0
	v_fma_f32 v254, -v56, v129, v254
	s_waitcnt lgkmcnt(1)
	v_fma_f32 v255, -v57, v130, v255
	v_fma_f32 v0, -v58, v131, v0
	v_fma_f32 v254, -v59, v132, v254
	v_fma_f32 v255, -v60, v133, v255
	ds_read_b128 v[122:125], v1 offset:31296
	s_waitcnt lgkmcnt(1)
	v_fma_f32 v0, -v61, v220, v0
	v_fma_f32 v254, -v62, v221, v254
	v_fma_f32 v255, -v63, v222, v255
	v_fma_f32 v0, -v70, v223, v0
	s_waitcnt lgkmcnt(0)
	v_fma_f32 v254, -v68, v122, v254
	v_fma_f32 v255, -v69, v123, v255
	v_fma_f32 v0, -v66, v124, v0
	v_fma_f32 v254, -v67, v125, v254
	ds_read_b128 v[122:125], v1 offset:31312
	s_waitcnt lgkmcnt(0)
	v_fma_f32 v255, -v64, v122, v255
	v_fma_f32 v0, -v65, v123, v0
	v_fma_f32 v254, -v52, v124, v254
	v_fma_f32 v255, -v53, v125, v255
	ds_read_b128 v[122:125], v1 offset:31328
	s_waitcnt lgkmcnt(0)
	v_fma_f32 v0, -v48, v122, v0
	v_fma_f32 v254, -v49, v123, v254
	v_fma_f32 v255, -v46, v124, v255
	v_fma_f32 v0, -v47, v125, v0
	ds_read_b128 v[122:125], v1 offset:31344
	s_waitcnt lgkmcnt(0)
	v_fma_f32 v254, -v44, v122, v254
	v_fma_f32 v255, -v45, v123, v255
	v_fma_f32 v0, -v42, v124, v0
	v_fma_f32 v254, -v43, v125, v254
	ds_read_b128 v[122:125], v1 offset:31360
	s_waitcnt lgkmcnt(0)
	v_fma_f32 v255, -v40, v122, v255
	v_fma_f32 v0, -v41, v123, v0
	v_fma_f32 v254, -v38, v124, v254
	v_fma_f32 v255, -v39, v125, v255
	ds_read_b128 v[122:125], v1 offset:31376
	s_waitcnt lgkmcnt(0)
	v_fma_f32 v0, -v36, v122, v0
	v_fma_f32 v254, -v37, v123, v254
	v_fma_f32 v255, -v34, v124, v255
	v_fma_f32 v0, -v35, v125, v0
	ds_read_b128 v[122:125], v1 offset:31392
	s_waitcnt lgkmcnt(0)
	v_fma_f32 v254, -v32, v122, v254
	v_fma_f32 v255, -v33, v123, v255
	v_fma_f32 v0, -v30, v124, v0
	v_fma_f32 v254, -v31, v125, v254
	ds_read_b128 v[122:125], v1 offset:31408
	s_waitcnt lgkmcnt(0)
	v_fma_f32 v255, -v28, v122, v255
	v_fma_f32 v0, -v29, v123, v0
	v_fma_f32 v254, -v26, v124, v254
	v_fma_f32 v255, -v27, v125, v255
	ds_read_b128 v[122:125], v1 offset:31424
	s_waitcnt lgkmcnt(0)
	v_fma_f32 v0, -v24, v122, v0
	v_fma_f32 v254, -v25, v123, v254
	v_fma_f32 v255, -v22, v124, v255
	v_fma_f32 v0, -v23, v125, v0
	ds_read_b128 v[122:125], v1 offset:31440
	s_waitcnt lgkmcnt(0)
	v_fma_f32 v254, -v20, v122, v254
	v_fma_f32 v255, -v21, v123, v255
	ds_read_b64 v[122:123], v1 offset:31456
	v_fma_f32 v0, -v18, v124, v0
	v_fma_f32 v254, -v19, v125, v254
	s_waitcnt lgkmcnt(0)
	v_fma_f32 v255, -v16, v122, v255
	v_fma_f32 v0, -v17, v123, v0
	v_add_f32_e32 v254, v0, v254
	v_add_f32_e32 v14, v254, v255
	ds_read_b128 v[122:125], v1 offset:31488
	ds_read_b128 v[126:129], v1 offset:31504
	ds_read_b128 v[130:133], v1 offset:31520
	ds_read_b128 v[220:223], v1 offset:31536
	s_waitcnt lgkmcnt(3)
	v_fma_f32 v0, -v2, v122, v15
	v_mul_f32_e64 v254, -v3, v123
	v_mul_f32_e64 v255, -v9, v124
	v_fma_f32 v0, -v50, v125, v0
	s_waitcnt lgkmcnt(2)
	v_fma_f32 v254, -v51, v126, v254
	v_fma_f32 v255, -v54, v127, v255
	v_fma_f32 v0, -v55, v128, v0
	v_fma_f32 v254, -v56, v129, v254
	s_waitcnt lgkmcnt(1)
	v_fma_f32 v255, -v57, v130, v255
	v_fma_f32 v0, -v58, v131, v0
	v_fma_f32 v254, -v59, v132, v254
	v_fma_f32 v255, -v60, v133, v255
	ds_read_b128 v[122:125], v1 offset:31552
	s_waitcnt lgkmcnt(1)
	v_fma_f32 v0, -v61, v220, v0
	v_fma_f32 v254, -v62, v221, v254
	v_fma_f32 v255, -v63, v222, v255
	v_fma_f32 v0, -v70, v223, v0
	s_waitcnt lgkmcnt(0)
	v_fma_f32 v254, -v68, v122, v254
	v_fma_f32 v255, -v69, v123, v255
	v_fma_f32 v0, -v66, v124, v0
	v_fma_f32 v254, -v67, v125, v254
	ds_read_b128 v[122:125], v1 offset:31568
	s_waitcnt lgkmcnt(0)
	v_fma_f32 v255, -v64, v122, v255
	v_fma_f32 v0, -v65, v123, v0
	v_fma_f32 v254, -v52, v124, v254
	v_fma_f32 v255, -v53, v125, v255
	ds_read_b128 v[122:125], v1 offset:31584
	s_waitcnt lgkmcnt(0)
	v_fma_f32 v0, -v48, v122, v0
	v_fma_f32 v254, -v49, v123, v254
	v_fma_f32 v255, -v46, v124, v255
	v_fma_f32 v0, -v47, v125, v0
	ds_read_b128 v[122:125], v1 offset:31600
	s_waitcnt lgkmcnt(0)
	v_fma_f32 v254, -v44, v122, v254
	v_fma_f32 v255, -v45, v123, v255
	v_fma_f32 v0, -v42, v124, v0
	v_fma_f32 v254, -v43, v125, v254
	ds_read_b128 v[122:125], v1 offset:31616
	s_waitcnt lgkmcnt(0)
	v_fma_f32 v255, -v40, v122, v255
	v_fma_f32 v0, -v41, v123, v0
	v_fma_f32 v254, -v38, v124, v254
	v_fma_f32 v255, -v39, v125, v255
	ds_read_b128 v[122:125], v1 offset:31632
	s_waitcnt lgkmcnt(0)
	v_fma_f32 v0, -v36, v122, v0
	v_fma_f32 v254, -v37, v123, v254
	v_fma_f32 v255, -v34, v124, v255
	v_fma_f32 v0, -v35, v125, v0
	ds_read_b128 v[122:125], v1 offset:31648
	s_waitcnt lgkmcnt(0)
	v_fma_f32 v254, -v32, v122, v254
	v_fma_f32 v255, -v33, v123, v255
	v_fma_f32 v0, -v30, v124, v0
	v_fma_f32 v254, -v31, v125, v254
	ds_read_b128 v[122:125], v1 offset:31664
	s_waitcnt lgkmcnt(0)
	v_fma_f32 v255, -v28, v122, v255
	v_fma_f32 v0, -v29, v123, v0
	v_fma_f32 v254, -v26, v124, v254
	v_fma_f32 v255, -v27, v125, v255
	ds_read_b128 v[122:125], v1 offset:31680
	s_waitcnt lgkmcnt(0)
	v_fma_f32 v0, -v24, v122, v0
	v_fma_f32 v254, -v25, v123, v254
	v_fma_f32 v255, -v22, v124, v255
	v_fma_f32 v0, -v23, v125, v0
	ds_read_b128 v[122:125], v1 offset:31696
	s_waitcnt lgkmcnt(0)
	v_fma_f32 v254, -v20, v122, v254
	v_fma_f32 v255, -v21, v123, v255
	v_fma_f32 v0, -v18, v124, v0
	ds_read_b96 v[122:124], v1 offset:31712
	v_fma_f32 v254, -v19, v125, v254
	s_waitcnt lgkmcnt(0)
	v_fma_f32 v255, -v16, v122, v255
	v_fma_f32 v0, -v17, v123, v0
	v_fma_f32 v254, -v14, v124, v254
	v_add_f32_e32 v254, v0, v254
	v_add_f32_e32 v15, v254, v255
	ds_read_b128 v[122:125], v1 offset:31744
	ds_read_b128 v[126:129], v1 offset:31760
	ds_read_b128 v[130:133], v1 offset:31776
	ds_read_b128 v[220:223], v1 offset:31792
	s_waitcnt lgkmcnt(3)
	v_fma_f32 v0, -v2, v122, v12
	v_mul_f32_e64 v254, -v3, v123
	v_mul_f32_e64 v255, -v9, v124
	v_fma_f32 v0, -v50, v125, v0
	s_waitcnt lgkmcnt(2)
	v_fma_f32 v254, -v51, v126, v254
	v_fma_f32 v255, -v54, v127, v255
	v_fma_f32 v0, -v55, v128, v0
	v_fma_f32 v254, -v56, v129, v254
	s_waitcnt lgkmcnt(1)
	v_fma_f32 v255, -v57, v130, v255
	v_fma_f32 v0, -v58, v131, v0
	v_fma_f32 v254, -v59, v132, v254
	v_fma_f32 v255, -v60, v133, v255
	ds_read_b128 v[122:125], v1 offset:31808
	s_waitcnt lgkmcnt(1)
	v_fma_f32 v0, -v61, v220, v0
	v_fma_f32 v254, -v62, v221, v254
	v_fma_f32 v255, -v63, v222, v255
	v_fma_f32 v0, -v70, v223, v0
	s_waitcnt lgkmcnt(0)
	v_fma_f32 v254, -v68, v122, v254
	v_fma_f32 v255, -v69, v123, v255
	v_fma_f32 v0, -v66, v124, v0
	v_fma_f32 v254, -v67, v125, v254
	ds_read_b128 v[122:125], v1 offset:31824
	s_waitcnt lgkmcnt(0)
	v_fma_f32 v255, -v64, v122, v255
	v_fma_f32 v0, -v65, v123, v0
	v_fma_f32 v254, -v52, v124, v254
	v_fma_f32 v255, -v53, v125, v255
	ds_read_b128 v[122:125], v1 offset:31840
	s_waitcnt lgkmcnt(0)
	v_fma_f32 v0, -v48, v122, v0
	v_fma_f32 v254, -v49, v123, v254
	v_fma_f32 v255, -v46, v124, v255
	v_fma_f32 v0, -v47, v125, v0
	ds_read_b128 v[122:125], v1 offset:31856
	s_waitcnt lgkmcnt(0)
	v_fma_f32 v254, -v44, v122, v254
	v_fma_f32 v255, -v45, v123, v255
	v_fma_f32 v0, -v42, v124, v0
	v_fma_f32 v254, -v43, v125, v254
	ds_read_b128 v[122:125], v1 offset:31872
	s_waitcnt lgkmcnt(0)
	v_fma_f32 v255, -v40, v122, v255
	v_fma_f32 v0, -v41, v123, v0
	v_fma_f32 v254, -v38, v124, v254
	v_fma_f32 v255, -v39, v125, v255
	ds_read_b128 v[122:125], v1 offset:31888
	s_waitcnt lgkmcnt(0)
	v_fma_f32 v0, -v36, v122, v0
	v_fma_f32 v254, -v37, v123, v254
	v_fma_f32 v255, -v34, v124, v255
	v_fma_f32 v0, -v35, v125, v0
	ds_read_b128 v[122:125], v1 offset:31904
	s_waitcnt lgkmcnt(0)
	v_fma_f32 v254, -v32, v122, v254
	v_fma_f32 v255, -v33, v123, v255
	v_fma_f32 v0, -v30, v124, v0
	v_fma_f32 v254, -v31, v125, v254
	ds_read_b128 v[122:125], v1 offset:31920
	s_waitcnt lgkmcnt(0)
	v_fma_f32 v255, -v28, v122, v255
	v_fma_f32 v0, -v29, v123, v0
	v_fma_f32 v254, -v26, v124, v254
	v_fma_f32 v255, -v27, v125, v255
	ds_read_b128 v[122:125], v1 offset:31936
	s_waitcnt lgkmcnt(0)
	v_fma_f32 v0, -v24, v122, v0
	v_fma_f32 v254, -v25, v123, v254
	v_fma_f32 v255, -v22, v124, v255
	v_fma_f32 v0, -v23, v125, v0
	ds_read_b128 v[122:125], v1 offset:31952
	s_waitcnt lgkmcnt(0)
	v_fma_f32 v254, -v20, v122, v254
	v_fma_f32 v255, -v21, v123, v255
	v_fma_f32 v0, -v18, v124, v0
	v_fma_f32 v254, -v19, v125, v254
	ds_read_b128 v[122:125], v1 offset:31968
	s_waitcnt lgkmcnt(0)
	v_fma_f32 v255, -v16, v122, v255
	v_fma_f32 v0, -v17, v123, v0
	v_fma_f32 v254, -v14, v124, v254
	v_fma_f32 v255, -v15, v125, v255
	v_add_f32_e32 v254, v0, v254
	v_add_f32_e32 v12, v254, v255
	ds_read_b128 v[122:125], v1 offset:32000
	ds_read_b128 v[126:129], v1 offset:32016
	ds_read_b128 v[130:133], v1 offset:32032
	ds_read_b128 v[220:223], v1 offset:32048
	s_waitcnt lgkmcnt(3)
	v_fma_f32 v0, -v2, v122, v13
	v_mul_f32_e64 v254, -v3, v123
	v_mul_f32_e64 v255, -v9, v124
	v_fma_f32 v0, -v50, v125, v0
	s_waitcnt lgkmcnt(2)
	v_fma_f32 v254, -v51, v126, v254
	v_fma_f32 v255, -v54, v127, v255
	v_fma_f32 v0, -v55, v128, v0
	v_fma_f32 v254, -v56, v129, v254
	s_waitcnt lgkmcnt(1)
	v_fma_f32 v255, -v57, v130, v255
	v_fma_f32 v0, -v58, v131, v0
	v_fma_f32 v254, -v59, v132, v254
	v_fma_f32 v255, -v60, v133, v255
	ds_read_b128 v[122:125], v1 offset:32064
	ds_read_b32 v13, v1 offset:32240
	s_waitcnt lgkmcnt(2)
	v_fma_f32 v0, -v61, v220, v0
	v_fma_f32 v254, -v62, v221, v254
	v_fma_f32 v255, -v63, v222, v255
	v_fma_f32 v0, -v70, v223, v0
	s_waitcnt lgkmcnt(1)
	v_fma_f32 v254, -v68, v122, v254
	v_fma_f32 v255, -v69, v123, v255
	v_fma_f32 v0, -v66, v124, v0
	v_fma_f32 v254, -v67, v125, v254
	ds_read_b128 v[122:125], v1 offset:32080
	s_waitcnt lgkmcnt(0)
	v_fma_f32 v255, -v64, v122, v255
	v_fma_f32 v0, -v65, v123, v0
	v_fma_f32 v254, -v52, v124, v254
	v_fma_f32 v255, -v53, v125, v255
	ds_read_b128 v[122:125], v1 offset:32096
	s_waitcnt lgkmcnt(0)
	v_fma_f32 v0, -v48, v122, v0
	v_fma_f32 v254, -v49, v123, v254
	v_fma_f32 v255, -v46, v124, v255
	v_fma_f32 v0, -v47, v125, v0
	ds_read_b128 v[122:125], v1 offset:32112
	s_waitcnt lgkmcnt(0)
	v_fma_f32 v254, -v44, v122, v254
	v_fma_f32 v255, -v45, v123, v255
	v_fma_f32 v0, -v42, v124, v0
	v_fma_f32 v254, -v43, v125, v254
	ds_read_b128 v[122:125], v1 offset:32128
	s_waitcnt lgkmcnt(0)
	v_fma_f32 v255, -v40, v122, v255
	v_fma_f32 v0, -v41, v123, v0
	v_fma_f32 v254, -v38, v124, v254
	v_fma_f32 v255, -v39, v125, v255
	ds_read_b128 v[122:125], v1 offset:32144
	s_waitcnt lgkmcnt(0)
	v_fma_f32 v0, -v36, v122, v0
	v_fma_f32 v254, -v37, v123, v254
	v_fma_f32 v255, -v34, v124, v255
	v_fma_f32 v0, -v35, v125, v0
	ds_read_b128 v[122:125], v1 offset:32160
	s_waitcnt lgkmcnt(0)
	v_fma_f32 v254, -v32, v122, v254
	v_fma_f32 v255, -v33, v123, v255
	v_fma_f32 v0, -v30, v124, v0
	v_fma_f32 v254, -v31, v125, v254
	ds_read_b128 v[122:125], v1 offset:32176
	s_waitcnt lgkmcnt(0)
	v_fma_f32 v255, -v28, v122, v255
	v_fma_f32 v0, -v29, v123, v0
	v_fma_f32 v254, -v26, v124, v254
	v_fma_f32 v255, -v27, v125, v255
	ds_read_b128 v[122:125], v1 offset:32192
	s_waitcnt lgkmcnt(0)
	v_fma_f32 v0, -v24, v122, v0
	v_fma_f32 v254, -v25, v123, v254
	v_fma_f32 v255, -v22, v124, v255
	v_fma_f32 v0, -v23, v125, v0
	ds_read_b128 v[122:125], v1 offset:32208
	s_waitcnt lgkmcnt(0)
	v_fma_f32 v254, -v20, v122, v254
	v_fma_f32 v255, -v21, v123, v255
	v_fma_f32 v0, -v18, v124, v0
	v_fma_f32 v254, -v19, v125, v254
	ds_read_b128 v[122:125], v1 offset:32224
	s_waitcnt lgkmcnt(0)
	v_fma_f32 v255, -v16, v122, v255
	v_fma_f32 v0, -v17, v123, v0
	v_fma_f32 v254, -v14, v124, v254
	v_fma_f32 v255, -v15, v125, v255
	v_fma_f32 v0, -v12, v13, v0
	v_add_f32_e32 v254, v0, v254
	v_add_f32_e32 v13, v254, v255
	ds_read_b128 v[122:125], v1 offset:32256
	ds_read_b128 v[126:129], v1 offset:32272
	ds_read_b128 v[130:133], v1 offset:32288
	ds_read_b128 v[220:223], v1 offset:32304
	s_waitcnt lgkmcnt(3)
	v_fma_f32 v0, -v2, v122, v10
	v_mul_f32_e64 v254, -v3, v123
	v_mul_f32_e64 v255, -v9, v124
	v_fma_f32 v0, -v50, v125, v0
	s_waitcnt lgkmcnt(2)
	v_fma_f32 v254, -v51, v126, v254
	v_fma_f32 v255, -v54, v127, v255
	v_fma_f32 v0, -v55, v128, v0
	v_fma_f32 v254, -v56, v129, v254
	s_waitcnt lgkmcnt(1)
	v_fma_f32 v255, -v57, v130, v255
	v_fma_f32 v0, -v58, v131, v0
	v_fma_f32 v254, -v59, v132, v254
	v_fma_f32 v255, -v60, v133, v255
	ds_read_b128 v[122:125], v1 offset:32320
	s_waitcnt lgkmcnt(1)
	v_fma_f32 v0, -v61, v220, v0
	v_fma_f32 v254, -v62, v221, v254
	v_fma_f32 v255, -v63, v222, v255
	v_fma_f32 v0, -v70, v223, v0
	s_waitcnt lgkmcnt(0)
	v_fma_f32 v254, -v68, v122, v254
	v_fma_f32 v255, -v69, v123, v255
	v_fma_f32 v0, -v66, v124, v0
	v_fma_f32 v254, -v67, v125, v254
	ds_read_b128 v[122:125], v1 offset:32336
	s_waitcnt lgkmcnt(0)
	v_fma_f32 v255, -v64, v122, v255
	v_fma_f32 v0, -v65, v123, v0
	v_fma_f32 v254, -v52, v124, v254
	v_fma_f32 v255, -v53, v125, v255
	ds_read_b128 v[122:125], v1 offset:32352
	s_waitcnt lgkmcnt(0)
	v_fma_f32 v0, -v48, v122, v0
	v_fma_f32 v254, -v49, v123, v254
	v_fma_f32 v255, -v46, v124, v255
	v_fma_f32 v0, -v47, v125, v0
	ds_read_b128 v[122:125], v1 offset:32368
	s_waitcnt lgkmcnt(0)
	v_fma_f32 v254, -v44, v122, v254
	v_fma_f32 v255, -v45, v123, v255
	v_fma_f32 v0, -v42, v124, v0
	v_fma_f32 v254, -v43, v125, v254
	ds_read_b128 v[122:125], v1 offset:32384
	s_waitcnt lgkmcnt(0)
	v_fma_f32 v255, -v40, v122, v255
	v_fma_f32 v0, -v41, v123, v0
	v_fma_f32 v254, -v38, v124, v254
	v_fma_f32 v255, -v39, v125, v255
	ds_read_b128 v[122:125], v1 offset:32400
	s_waitcnt lgkmcnt(0)
	v_fma_f32 v0, -v36, v122, v0
	v_fma_f32 v254, -v37, v123, v254
	v_fma_f32 v255, -v34, v124, v255
	v_fma_f32 v0, -v35, v125, v0
	ds_read_b128 v[122:125], v1 offset:32416
	s_waitcnt lgkmcnt(0)
	v_fma_f32 v254, -v32, v122, v254
	v_fma_f32 v255, -v33, v123, v255
	v_fma_f32 v0, -v30, v124, v0
	v_fma_f32 v254, -v31, v125, v254
	ds_read_b128 v[122:125], v1 offset:32432
	s_waitcnt lgkmcnt(0)
	v_fma_f32 v255, -v28, v122, v255
	v_fma_f32 v0, -v29, v123, v0
	v_fma_f32 v254, -v26, v124, v254
	v_fma_f32 v255, -v27, v125, v255
	ds_read_b128 v[122:125], v1 offset:32448
	s_waitcnt lgkmcnt(0)
	v_fma_f32 v0, -v24, v122, v0
	v_fma_f32 v254, -v25, v123, v254
	v_fma_f32 v255, -v22, v124, v255
	v_fma_f32 v0, -v23, v125, v0
	ds_read_b128 v[122:125], v1 offset:32464
	s_waitcnt lgkmcnt(0)
	v_fma_f32 v254, -v20, v122, v254
	v_fma_f32 v255, -v21, v123, v255
	v_fma_f32 v0, -v18, v124, v0
	v_fma_f32 v254, -v19, v125, v254
	ds_read_b128 v[122:125], v1 offset:32480
	s_waitcnt lgkmcnt(0)
	v_fma_f32 v255, -v16, v122, v255
	v_fma_f32 v0, -v17, v123, v0
	ds_read_b64 v[122:123], v1 offset:32496
	v_fma_f32 v254, -v14, v124, v254
	v_fma_f32 v255, -v15, v125, v255
	s_waitcnt lgkmcnt(0)
	v_fma_f32 v0, -v12, v122, v0
	v_fma_f32 v254, -v13, v123, v254
	v_add_f32_e32 v254, v0, v254
	v_add_f32_e32 v10, v254, v255
	ds_read_b128 v[122:125], v1 offset:32512
	ds_read_b128 v[126:129], v1 offset:32528
	ds_read_b128 v[130:133], v1 offset:32544
	ds_read_b128 v[220:223], v1 offset:32560
	s_waitcnt lgkmcnt(3)
	v_fma_f32 v0, -v2, v122, v11
	v_mul_f32_e64 v254, -v3, v123
	v_mul_f32_e64 v255, -v9, v124
	v_fma_f32 v0, -v50, v125, v0
	s_waitcnt lgkmcnt(2)
	v_fma_f32 v254, -v51, v126, v254
	v_fma_f32 v255, -v54, v127, v255
	v_fma_f32 v0, -v55, v128, v0
	v_fma_f32 v254, -v56, v129, v254
	s_waitcnt lgkmcnt(1)
	v_fma_f32 v255, -v57, v130, v255
	v_fma_f32 v0, -v58, v131, v0
	v_fma_f32 v254, -v59, v132, v254
	v_fma_f32 v255, -v60, v133, v255
	ds_read_b128 v[122:125], v1 offset:32576
	s_waitcnt lgkmcnt(1)
	v_fma_f32 v0, -v61, v220, v0
	v_fma_f32 v254, -v62, v221, v254
	v_fma_f32 v255, -v63, v222, v255
	v_fma_f32 v0, -v70, v223, v0
	s_waitcnt lgkmcnt(0)
	v_fma_f32 v254, -v68, v122, v254
	v_fma_f32 v255, -v69, v123, v255
	v_fma_f32 v0, -v66, v124, v0
	v_fma_f32 v254, -v67, v125, v254
	ds_read_b128 v[122:125], v1 offset:32592
	s_waitcnt lgkmcnt(0)
	v_fma_f32 v255, -v64, v122, v255
	v_fma_f32 v0, -v65, v123, v0
	v_fma_f32 v254, -v52, v124, v254
	v_fma_f32 v255, -v53, v125, v255
	ds_read_b128 v[122:125], v1 offset:32608
	s_waitcnt lgkmcnt(0)
	v_fma_f32 v0, -v48, v122, v0
	v_fma_f32 v254, -v49, v123, v254
	v_fma_f32 v255, -v46, v124, v255
	v_fma_f32 v0, -v47, v125, v0
	ds_read_b128 v[122:125], v1 offset:32624
	s_waitcnt lgkmcnt(0)
	v_fma_f32 v254, -v44, v122, v254
	v_fma_f32 v255, -v45, v123, v255
	v_fma_f32 v0, -v42, v124, v0
	v_fma_f32 v254, -v43, v125, v254
	ds_read_b128 v[122:125], v1 offset:32640
	s_waitcnt lgkmcnt(0)
	v_fma_f32 v255, -v40, v122, v255
	v_fma_f32 v0, -v41, v123, v0
	v_fma_f32 v254, -v38, v124, v254
	v_fma_f32 v255, -v39, v125, v255
	ds_read_b128 v[122:125], v1 offset:32656
	s_waitcnt lgkmcnt(0)
	v_fma_f32 v0, -v36, v122, v0
	v_fma_f32 v254, -v37, v123, v254
	v_fma_f32 v255, -v34, v124, v255
	v_fma_f32 v0, -v35, v125, v0
	ds_read_b128 v[122:125], v1 offset:32672
	s_waitcnt lgkmcnt(0)
	v_fma_f32 v254, -v32, v122, v254
	v_fma_f32 v255, -v33, v123, v255
	v_fma_f32 v0, -v30, v124, v0
	v_fma_f32 v254, -v31, v125, v254
	ds_read_b128 v[122:125], v1 offset:32688
	s_waitcnt lgkmcnt(0)
	v_fma_f32 v255, -v28, v122, v255
	v_fma_f32 v0, -v29, v123, v0
	v_fma_f32 v254, -v26, v124, v254
	v_fma_f32 v255, -v27, v125, v255
	ds_read_b128 v[122:125], v1 offset:32704
	s_waitcnt lgkmcnt(0)
	v_fma_f32 v0, -v24, v122, v0
	v_fma_f32 v254, -v25, v123, v254
	v_fma_f32 v255, -v22, v124, v255
	v_fma_f32 v0, -v23, v125, v0
	ds_read_b128 v[122:125], v1 offset:32720
	s_waitcnt lgkmcnt(0)
	v_fma_f32 v254, -v20, v122, v254
	v_fma_f32 v255, -v21, v123, v255
	v_fma_f32 v0, -v18, v124, v0
	v_fma_f32 v254, -v19, v125, v254
	ds_read_b128 v[122:125], v1 offset:32736
	s_waitcnt lgkmcnt(0)
	v_fma_f32 v255, -v16, v122, v255
	v_fma_f32 v0, -v17, v123, v0
	v_fma_f32 v254, -v14, v124, v254
	ds_read_b96 v[122:124], v1 offset:32752
	v_fma_f32 v255, -v15, v125, v255
	s_waitcnt lgkmcnt(0)
	v_fma_f32 v0, -v12, v122, v0
	v_fma_f32 v254, -v13, v123, v254
	v_fma_f32 v255, -v10, v124, v255
	v_add_f32_e32 v254, v0, v254
	v_add_f32_e32 v11, v254, v255
	v_lshl_add_u64 v[122:123], v[162:163], 1, s[92:93]
	v_lshlrev_b32_e32 v0, 1, v8
	v_lshl_add_u64 v[122:123], v[122:123], 0, v[0:1]
	v_cvt_pk_bf16_f32 v0, v2, s0
	global_store_short v[122:123], v0, off
	v_cvt_pk_bf16_f32 v0, v3, s0
	global_store_short v[122:123], v0, off offset:256
	v_cvt_pk_bf16_f32 v0, v9, s0
	global_store_short v[122:123], v0, off offset:512
	v_cvt_pk_bf16_f32 v0, v50, s0
	global_store_short v[122:123], v0, off offset:768
	v_cvt_pk_bf16_f32 v0, v51, s0
	global_store_short v[122:123], v0, off offset:1024
	v_cvt_pk_bf16_f32 v0, v54, s0
	global_store_short v[122:123], v0, off offset:1280
	v_cvt_pk_bf16_f32 v0, v55, s0
	global_store_short v[122:123], v0, off offset:1536
	v_cvt_pk_bf16_f32 v0, v56, s0
	global_store_short v[122:123], v0, off offset:1792
	v_cvt_pk_bf16_f32 v0, v57, s0
	global_store_short v[122:123], v0, off offset:2048
	v_cvt_pk_bf16_f32 v0, v58, s0
	global_store_short v[122:123], v0, off offset:2304
	v_cvt_pk_bf16_f32 v0, v59, s0
	global_store_short v[122:123], v0, off offset:2560
	v_cvt_pk_bf16_f32 v0, v60, s0
	global_store_short v[122:123], v0, off offset:2816
	v_cvt_pk_bf16_f32 v0, v61, s0
	global_store_short v[122:123], v0, off offset:3072
	v_cvt_pk_bf16_f32 v0, v62, s0
	global_store_short v[122:123], v0, off offset:3328
	v_cvt_pk_bf16_f32 v0, v63, s0
	global_store_short v[122:123], v0, off offset:3584
	v_cvt_pk_bf16_f32 v0, v70, s0
	global_store_short v[122:123], v0, off offset:3840
	v_cvt_pk_bf16_f32 v0, v68, s0
	s_movk_i32 s0, 0x1000
	v_add_co_u32_e32 v2, vcc, s0, v122
	s_movk_i32 s0, 0x2000
	s_nop 0
	v_addc_co_u32_e32 v3, vcc, 0, v123, vcc
	v_add_co_u32_e32 v8, vcc, s0, v122
	s_nop 1
	v_addc_co_u32_e32 v9, vcc, 0, v123, vcc
	global_store_short v[8:9], v0, off offset:-4096
	v_cvt_pk_bf16_f32 v0, v69, s0
	global_store_short v[2:3], v0, off offset:256
	v_cvt_pk_bf16_f32 v0, v66, s0
	global_store_short v[2:3], v0, off offset:512
	v_cvt_pk_bf16_f32 v0, v67, s0
	global_store_short v[2:3], v0, off offset:768
	v_cvt_pk_bf16_f32 v0, v64, s0
	global_store_short v[2:3], v0, off offset:1024
	v_cvt_pk_bf16_f32 v0, v65, s0
	global_store_short v[2:3], v0, off offset:1280
	v_cvt_pk_bf16_f32 v0, v52, s0
	global_store_short v[2:3], v0, off offset:1536
	v_cvt_pk_bf16_f32 v0, v53, s0
	global_store_short v[2:3], v0, off offset:1792
	v_cvt_pk_bf16_f32 v0, v48, s0
	global_store_short v[2:3], v0, off offset:2048
	v_cvt_pk_bf16_f32 v0, v49, s0
	global_store_short v[2:3], v0, off offset:2304
	v_cvt_pk_bf16_f32 v0, v46, s0
	global_store_short v[2:3], v0, off offset:2560
	v_cvt_pk_bf16_f32 v0, v47, s0
	global_store_short v[2:3], v0, off offset:2816
	v_cvt_pk_bf16_f32 v0, v44, s0
	global_store_short v[2:3], v0, off offset:3072
	v_cvt_pk_bf16_f32 v0, v45, s0
	global_store_short v[2:3], v0, off offset:3328
	v_cvt_pk_bf16_f32 v0, v42, s0
	global_store_short v[2:3], v0, off offset:3584
	v_cvt_pk_bf16_f32 v0, v43, s0
	global_store_short v[2:3], v0, off offset:3840
	v_cvt_pk_bf16_f32 v0, v40, s0
	global_store_short v[8:9], v0, off
	v_cvt_pk_bf16_f32 v0, v41, s0
	global_store_short v[8:9], v0, off offset:256
	v_cvt_pk_bf16_f32 v0, v38, s0
	global_store_short v[8:9], v0, off offset:512
	v_cvt_pk_bf16_f32 v0, v39, s0
	global_store_short v[8:9], v0, off offset:768
	v_cvt_pk_bf16_f32 v0, v36, s0
	global_store_short v[8:9], v0, off offset:1024
	v_cvt_pk_bf16_f32 v0, v37, s0
	global_store_short v[8:9], v0, off offset:1280
	v_cvt_pk_bf16_f32 v0, v34, s0
	global_store_short v[8:9], v0, off offset:1536
	v_cvt_pk_bf16_f32 v0, v35, s0
	global_store_short v[8:9], v0, off offset:1792
	v_cvt_pk_bf16_f32 v0, v32, s0
	global_store_short v[8:9], v0, off offset:2048
	v_cvt_pk_bf16_f32 v0, v33, s0
	global_store_short v[8:9], v0, off offset:2304
	v_cvt_pk_bf16_f32 v0, v30, s0
	global_store_short v[8:9], v0, off offset:2560
	v_cvt_pk_bf16_f32 v0, v31, s0
	global_store_short v[8:9], v0, off offset:2816
	v_cvt_pk_bf16_f32 v0, v28, s0
	global_store_short v[8:9], v0, off offset:3072
	v_cvt_pk_bf16_f32 v0, v29, s0
	global_store_short v[8:9], v0, off offset:3328
	v_cvt_pk_bf16_f32 v0, v26, s0
	global_store_short v[8:9], v0, off offset:3584
	v_cvt_pk_bf16_f32 v0, v27, s0
	global_store_short v[8:9], v0, off offset:3840
	v_cvt_pk_bf16_f32 v0, v24, s0
	s_movk_i32 s0, 0x3000
	v_add_co_u32_e32 v2, vcc, s0, v122
	s_nop 1
	v_addc_co_u32_e32 v3, vcc, 0, v123, vcc
	global_store_short v[2:3], v0, off
	v_cvt_pk_bf16_f32 v0, v25, s0
	global_store_short v[2:3], v0, off offset:256
	v_cvt_pk_bf16_f32 v0, v22, s0
	global_store_short v[2:3], v0, off offset:512
	v_cvt_pk_bf16_f32 v0, v23, s0
	global_store_short v[2:3], v0, off offset:768
	v_cvt_pk_bf16_f32 v0, v20, s0
	global_store_short v[2:3], v0, off offset:1024
	v_cvt_pk_bf16_f32 v0, v21, s0
	global_store_short v[2:3], v0, off offset:1280
	v_cvt_pk_bf16_f32 v0, v18, s0
	global_store_short v[2:3], v0, off offset:1536
	v_cvt_pk_bf16_f32 v0, v19, s0
	global_store_short v[2:3], v0, off offset:1792
	v_cvt_pk_bf16_f32 v0, v16, s0
	global_store_short v[2:3], v0, off offset:2048
	v_cvt_pk_bf16_f32 v0, v17, s0
	global_store_short v[2:3], v0, off offset:2304
	v_cvt_pk_bf16_f32 v0, v14, s0
	global_store_short v[2:3], v0, off offset:2560
	v_cvt_pk_bf16_f32 v0, v15, s0
	global_store_short v[2:3], v0, off offset:2816
	v_cvt_pk_bf16_f32 v0, v12, s0
	global_store_short v[2:3], v0, off offset:3072
	v_cvt_pk_bf16_f32 v0, v13, s0
	global_store_short v[2:3], v0, off offset:3328
	v_cvt_pk_bf16_f32 v0, v10, s0
	global_store_short v[2:3], v0, off offset:3584
	v_cvt_pk_bf16_f32 v0, v11, s0
	global_store_short v[2:3], v0, off offset:3840
	s_and_saveexec_b64 s[0:1], s[96:97]
	s_xor_b64 s[0:1], exec, s[0:1]
	s_cbranch_execz .LBB0_315
	ds_read_b32 v0, v1 offset:49916
	s_mov_b32 s65, s9
	v_readlane_b32 s68, v251, 8
	s_lshl_b64 s[14:15], s[64:65], 2
	v_readlane_b32 s76, v251, 16
	v_readlane_b32 s77, v251, 17
	s_add_u32 s14, s76, s14
	s_addc_u32 s15, s77, s15
	v_readlane_b32 s69, v251, 9
	v_readlane_b32 s70, v251, 10
	v_readlane_b32 s71, v251, 11
	v_readlane_b32 s72, v251, 12
	v_readlane_b32 s73, v251, 13
	v_readlane_b32 s74, v251, 14
	v_readlane_b32 s75, v251, 15
	v_readlane_b32 s78, v251, 18
	v_readlane_b32 s79, v251, 19
	v_readlane_b32 s80, v251, 20
	v_readlane_b32 s81, v251, 21
	v_readlane_b32 s82, v251, 22
	v_readlane_b32 s83, v251, 23
	s_waitcnt lgkmcnt(0)
	global_store_dword v1, v0, s[14:15]
